# tile remap + pipelined K-loop extended to zgemm and merge-gate GEMMs (all 128x128 GEMM phases)
# speedup vs baseline: 1.0375x; 1.0375x over previous
; #define GLOAD(ra, rb, koff)                                                        \
;   {                                                                                \
;     _Pragma("unroll") for (int j = 0; j < 4; j++) ra[j] = *(const u32x4*)(pa + j * sa32 + (koff));   \
;     _Pragma("unroll") for (int j = 0; j < NB_; j++) rb[j] = *(const u32x4*)(pbv[j] + (koff));         \
;   }
; template <int NT, bool PRE> ...
;     ...
;   const int wsw = ((tid & 7) ^ ((tid >> 4) & 7)) * 8;
;   const int rsw = (lane & 15) >> 1;
;     ...
;   if (!PRE) {
;     GLOAD(ra0, rb0, 0);
;     GLOAD(ra1, rb1, 64);
;   }
;   __syncthreads();
;   for (int k0 = 0; k0 < K; k0 += 128) {
;     LSTORE(ra0, rb0, 0);
;     __syncthreads();
; __device__ __forceinline__ void phase_zgemm(const Params& P, u16* sA, u16* sB) {
;   char* ws = opq(P.ws);
;   const int tq = TID();
;   const int T = 132 * 20, G = gridDim.x;
;   const int tail = T % G;
;   const bool split = tail > 0 && tail * 4 <= G;
;   const int Tfull = split ? T - tail : T;
;   for (int t = blockIdx.x; t < Tfull; t += G) zgemm_tile<4>(ws, (t % 132) * 128, (t / 132) * 128, sA, sB, tq);
.LBB0_230:
	s_cmp_lg_u32 s90, 0x200
	s_cbranch_scc1 .Lrm_zg_orig
	s_and_b32 s1, s28, 7
	s_lshl_b32 s1, s1, 6
	s_bfe_u32 s2, s28, 0x60003
	s_or_b32 s1, s1, s2
	s_andn2_b32 s2, s28, 0x1ff
	s_or_b32 s1, s1, s2
	s_cmp_lt_u32 s1, 2112
	s_cbranch_scc0 .Lrm_zg_b
	s_lshr_b32 s2, s1, 3
	s_mul_hi_u32 s2, s2, 0x3e0f83e1
	s_lshr_b32 s2, s2, 5
	s_mul_i32 s0, s2, 1056
	s_sub_i32 s1, s1, s0
	s_lshl_b32 s2, s2, 3
	s_and_b32 s0, s1, 7
	s_add_i32 s2, s2, s0
	s_lshr_b32 s0, s1, 3
	s_branch .Lrm_zg_done
.Lrm_zg_b:
	s_sub_i32 s1, s1, 2112
	s_cmp_lt_u32 s1, 396
	s_cbranch_scc0 .Lrm_zg_c
	s_mul_i32 s0, s1, 21846
	s_lshr_b32 s0, s0, 16
	s_mul_i32 s2, s0, 3
	s_sub_i32 s2, s1, s2
	s_add_i32 s2, s2, 16
	s_branch .Lrm_zg_done
.Lrm_zg_c:
	s_sub_i32 s0, s1, 396
	s_movk_i32 s2, 19
	s_branch .Lrm_zg_done
.Lrm_zg_orig:
	s_mul_hi_u32 s2, s28, 0x3e0f83e1
	s_lshr_b32 s2, s2, 5
	s_mul_i32 s1, s2, 0x84
	s_sub_i32 s0, s28, s1
.Lrm_zg_done:
	v_mov_b32_e32 v12, v169
	s_lshl_b32 s3, s0, 7
	s_lshl_b32 s0, s2, 7
	s_mov_b64 s[4:5], 0x10000
	v_ashrrev_i32_e32 v4, 3, v12
	v_add_u32_e32 v0, s0, v4
	v_lshlrev_b32_e32 v13, 4, v12
	v_and_b32_e32 v130, 0x70, v13
	v_ashrrev_i32_e32 v1, 31, v0
	v_lshl_add_u64 v[2:3], s[14:15], 0, v[130:131]
	v_lshlrev_b64 v[0:1], 11, v[0:1]
	v_lshl_add_u64 v[144:145], v[2:3], 0, v[0:1]
	v_add_u32_e32 v0, s3, v4
	v_ashrrev_i32_e32 v1, 31, v0
	v_lshlrev_b64 v[0:1], 11, v[0:1]
	v_lshl_add_u64 v[0:1], s[16:17], 0, v[0:1]
	v_lshl_add_u64 v[152:153], v[0:1], 0, v[130:131]
	v_add_co_u32_e32 v0, vcc, s33, v152
	v_lshl_add_u64 v[146:147], v[144:145], 0, s[4:5]
	s_nop 0
	v_addc_co_u32_e32 v1, vcc, 0, v153, vcc
	v_add_co_u32_e32 v2, vcc, s56, v152
	s_mov_b64 s[4:5], 0x20000
	s_nop 0
	v_addc_co_u32_e32 v3, vcc, 0, v153, vcc
	v_add_co_u32_e32 v4, vcc, s57, v152
	v_lshl_add_u64 v[148:149], v[144:145], 0, s[4:5]
	s_nop 0
	v_addc_co_u32_e32 v5, vcc, 0, v153, vcc
	v_add_co_u32_e32 v6, vcc, s33, v144
	s_mov_b64 s[4:5], 0x30000
	s_nop 0
	v_addc_co_u32_e32 v7, vcc, 0, v145, vcc
	v_add_co_u32_e32 v8, vcc, s56, v144
	v_lshl_add_u64 v[150:151], v[144:145], 0, s[4:5]
	s_nop 0
	v_addc_co_u32_e32 v9, vcc, 0, v145, vcc
	v_add_co_u32_e32 v10, vcc, s57, v144
	v_lshrrev_b32_e32 v14, 4, v12
	s_nop 0
	v_addc_co_u32_e32 v11, vcc, 0, v145, vcc
	global_load_dwordx4 v[64:67], v[8:9], off
	global_load_dwordx4 v[68:71], v[10:11], off
	global_load_dwordx4 v[120:123], v[0:1], off
	global_load_dwordx4 v[72:75], v[152:153], off offset:128
	global_load_dwordx4 v[112:115], v[2:3], off
	global_load_dwordx4 v[96:99], v[0:1], off offset:128
	global_load_dwordx4 v[116:119], v[4:5], off
	global_load_dwordx4 v[100:103], v[2:3], off offset:128
	global_load_dwordx4 v[84:87], v[6:7], off
	global_load_dwordx4 v[108:111], v[4:5], off offset:128
	global_load_dwordx4 v[104:107], v[144:145], off
	global_load_dwordx4 v[76:79], v[144:145], off offset:128
	global_load_dwordx4 v[80:83], v[146:147], off offset:128
	global_load_dwordx4 v[88:91], v[148:149], off offset:128
	global_load_dwordx4 v[124:127], v[152:153], off
	global_load_dwordx4 v[92:95], v[150:151], off offset:128
	v_xor_b32_e32 v15, v14, v12
	v_lshlrev_b32_e32 v1, 4, v15
	v_and_b32_e32 v1, 0x70, v1
	s_movk_i32 s1, 0xff80
	v_bfe_u32 v0, v12, 1, 3
	v_and_or_b32 v130, v13, s1, v1
	v_bfe_u32 v1, v12, 4, 2
	v_bitop3_b32 v2, v14, v0, 3 bitop3:0x6c
	v_lshlrev_b32_e32 v3, 6, v12
	v_lshlrev_b32_e32 v6, 7, v12
	v_bitop3_b32 v0, v1, v0, 4 bitop3:0x36
	v_and_b32_e32 v16, 15, v12
	v_lshlrev_b32_e32 v2, 4, v2
	v_and_b32_e32 v3, 0xffffe000, v3
	v_and_b32_e32 v6, 0x2000, v6
	v_lshlrev_b32_e32 v0, 4, v0
	v_lshlrev_b32_e32 v4, 7, v16
	v_or_b32_e32 v5, v2, v3
	v_or_b32_e32 v2, v2, v6
	v_or_b32_e32 v1, v0, v3
	v_or_b32_e32 v3, v0, v6
	v_mov_b32_e32 v0, 0
	v_add_u32_e32 v160, v5, v4
	v_add_u32_e32 v161, v2, v4
	v_add_u32_e32 v162, v1, v4
	v_add_u32_e32 v163, v3, v4
	v_mov_b32_e32 v1, v0
	v_mov_b32_e32 v2, v0
	v_mov_b32_e32 v3, v0
	v_mov_b32_e32 v16, v0
	v_mov_b32_e32 v17, v0
	v_mov_b32_e32 v18, v0
	v_mov_b32_e32 v19, v0
	v_mov_b32_e32 v32, v0
	v_mov_b32_e32 v33, v0
	v_mov_b32_e32 v34, v0
	v_mov_b32_e32 v35, v0
	s_waitcnt vmcnt(16)
	v_mov_b32_e32 v48, v0
	v_mov_b32_e32 v49, v0
	v_mov_b32_e32 v50, v0
	v_mov_b32_e32 v51, v0
	v_mov_b32_e32 v4, v0
	v_mov_b32_e32 v5, v0
	v_mov_b32_e32 v6, v0
	v_mov_b32_e32 v7, v0
	v_mov_b32_e32 v20, v0
	v_mov_b32_e32 v21, v0
	v_mov_b32_e32 v22, v0
	v_mov_b32_e32 v23, v0
	v_mov_b32_e32 v36, v0
	v_mov_b32_e32 v37, v0
	v_mov_b32_e32 v38, v0
	v_mov_b32_e32 v39, v0
	v_mov_b32_e32 v52, v0
	v_mov_b32_e32 v53, v0
	v_mov_b32_e32 v54, v0
	v_mov_b32_e32 v55, v0
	v_mov_b32_e32 v8, v0
	v_mov_b32_e32 v9, v0
	v_mov_b32_e32 v10, v0
	v_mov_b32_e32 v11, v0
	v_mov_b32_e32 v24, v0
	v_mov_b32_e32 v25, v0
	v_mov_b32_e32 v26, v0
	v_mov_b32_e32 v27, v0
	v_mov_b32_e32 v40, v0
	v_mov_b32_e32 v41, v0
	v_mov_b32_e32 v42, v0
	v_mov_b32_e32 v43, v0
	v_mov_b32_e32 v56, v0
	v_mov_b32_e32 v57, v0
	v_mov_b32_e32 v58, v0
	v_mov_b32_e32 v59, v0
	v_mov_b32_e32 v12, v0
	v_mov_b32_e32 v13, v0
	v_mov_b32_e32 v14, v0
	v_mov_b32_e32 v15, v0
	v_mov_b32_e32 v28, v0
	v_mov_b32_e32 v29, v0
	v_mov_b32_e32 v30, v0
	v_mov_b32_e32 v31, v0
	v_mov_b32_e32 v44, v0
	v_mov_b32_e32 v45, v0
	v_mov_b32_e32 v46, v0
	v_mov_b32_e32 v47, v0
	v_mov_b32_e32 v60, v0
	v_mov_b32_e32 v61, v0
	v_mov_b32_e32 v62, v0
	v_mov_b32_e32 v63, v0
	s_barrier
	s_waitcnt vmcnt(1)
	ds_write_b128 v130, v[124:127]
	ds_write_b128 v130, v[120:123] offset:4096
	ds_write_b128 v130, v[112:115] offset:8192
	ds_write_b128 v130, v[116:119] offset:12288
	ds_write_b128 v130, v[104:107] offset:16384
	ds_write_b128 v130, v[84:87] offset:20480
	ds_write_b128 v130, v[64:67] offset:24576
	ds_write_b128 v130, v[68:71] offset:28672
	s_waitcnt lgkmcnt(0)
	s_barrier
; #define GLOAD(ra, rb, koff)                                                        \
;   {                                                                                \
;     _Pragma("unroll") for (int j = 0; j < 4; j++) ra[j] = *(const u32x4*)(pa + j * sa32 + (koff));   \
;     _Pragma("unroll") for (int j = 0; j < NB_; j++) rb[j] = *(const u32x4*)(pbv[j] + (koff));         \
;   }
; template <int NT, bool PRE> ...
;     ...
;   const int wsw = ((tid & 7) ^ ((tid >> 4) & 7)) * 8;
;   const int rsw = (lane & 15) >> 1;
;     ...
;   if (!PRE) {
;     GLOAD(ra0, rb0, 0);
;     GLOAD(ra1, rb1, 64);
;   }
;   __syncthreads();
;   for (int k0 = 0; k0 < K; k0 += 128) {
;     LSTORE(ra0, rb0, 0);
;     __syncthreads();
;     GLOAD(ra0, rb0, min(k0 + 128, K - 128));
;     __builtin_amdgcn_sched_barrier(0);
;     COMPUTE(0);
.LBB0_231:
	s_add_i32 s4, s1, 0x100
	s_min_u32 s4, s4, 0x380
	s_lshl_b32 s54, s4, 1
	ds_read_b128 v[164:167], v160
	ds_read_b128 v[210:213], v161 offset:16384
	ds_read_b128 v[214:217], v161 offset:18432
	ds_read_b128 v[218:221], v161 offset:20480
	ds_read_b128 v[222:225], v161 offset:22528
	ds_read_b128 v[198:201], v160 offset:2048
	ds_read_b128 v[202:205], v160 offset:4096
	ds_read_b128 v[206:209], v160 offset:6144
	ds_read_b128 v[226:229], v162
	ds_read_b128 v[230:233], v162 offset:2048
	ds_read_b128 v[234:237], v162 offset:4096
	ds_read_b128 v[238:241], v162 offset:6144
	ds_read_b128 v[242:245], v163 offset:16384
	v_lshl_add_u64 v[112:113], v[152:153], 0, s[54:55]
	v_add_co_u32_e32 v114, vcc, s33, v112
	v_lshl_add_u64 v[64:65], v[144:145], 0, s[54:55]
	s_nop 0
	v_addc_co_u32_e32 v115, vcc, 0, v113, vcc
	v_add_co_u32_e32 v116, vcc, s56, v112
	v_lshl_add_u64 v[66:67], v[146:147], 0, s[54:55]
	s_nop 0
	v_addc_co_u32_e32 v117, vcc, 0, v113, vcc
	v_add_co_u32_e32 v118, vcc, s57, v112
	v_lshl_add_u64 v[68:69], v[148:149], 0, s[54:55]
	v_lshl_add_u64 v[70:71], v[150:151], 0, s[54:55]
	v_addc_co_u32_e32 v119, vcc, 0, v113, vcc
	s_addk_i32 s1, 0x80
	s_setprio 1
	s_waitcnt lgkmcnt(11)
	v_mfma_f32_16x16x32_bf16 v[60:63], v[210:213], v[164:167], v[60:63]
	s_waitcnt lgkmcnt(10)
	v_mfma_f32_16x16x32_bf16 v[44:47], v[214:217], v[164:167], v[44:47]
	s_waitcnt lgkmcnt(9)
	v_mfma_f32_16x16x32_bf16 v[28:31], v[218:221], v[164:167], v[28:31]
	s_waitcnt lgkmcnt(8)
	v_mfma_f32_16x16x32_bf16 v[12:15], v[222:225], v[164:167], v[12:15]
	ds_read_b128 v[164:167], v163 offset:18432
	global_load_dwordx4 v[104:107], v[64:65], off
	s_nop 0
	global_load_dwordx4 v[84:87], v[66:67], off
	s_waitcnt lgkmcnt(8)
	v_mfma_f32_16x16x32_bf16 v[56:59], v[210:213], v[198:201], v[56:59]
	v_mfma_f32_16x16x32_bf16 v[40:43], v[214:217], v[198:201], v[40:43]
	v_mfma_f32_16x16x32_bf16 v[24:27], v[218:221], v[198:201], v[24:27]
	v_mfma_f32_16x16x32_bf16 v[8:11], v[222:225], v[198:201], v[8:11]
	ds_read_b128 v[198:201], v163 offset:20480
	global_load_dwordx4 v[64:67], v[68:69], off
	s_nop 0
	global_load_dwordx4 v[68:71], v[70:71], off
	s_waitcnt lgkmcnt(8)
	v_mfma_f32_16x16x32_bf16 v[52:55], v[210:213], v[202:205], v[52:55]
	v_mfma_f32_16x16x32_bf16 v[36:39], v[214:217], v[202:205], v[36:39]
	v_mfma_f32_16x16x32_bf16 v[20:23], v[218:221], v[202:205], v[20:23]
	v_mfma_f32_16x16x32_bf16 v[4:7], v[222:225], v[202:205], v[4:7]
	ds_read_b128 v[202:205], v163 offset:22528
	global_load_dwordx4 v[124:127], v[112:113], off
	s_nop 0
	global_load_dwordx4 v[120:123], v[114:115], off
	s_waitcnt lgkmcnt(8)
	v_mfma_f32_16x16x32_bf16 v[48:51], v[210:213], v[206:209], v[48:51]
	v_mfma_f32_16x16x32_bf16 v[32:35], v[214:217], v[206:209], v[32:35]
	v_mfma_f32_16x16x32_bf16 v[16:19], v[218:221], v[206:209], v[16:19]
	v_mfma_f32_16x16x32_bf16 v[0:3], v[222:225], v[206:209], v[0:3]
	global_load_dwordx4 v[112:115], v[116:117], off
	s_nop 0
	global_load_dwordx4 v[116:119], v[118:119], off
	s_waitcnt lgkmcnt(3)
	v_mfma_f32_16x16x32_bf16 v[60:63], v[242:245], v[226:229], v[60:63]
	v_mfma_f32_16x16x32_bf16 v[56:59], v[242:245], v[230:233], v[56:59]
	v_mfma_f32_16x16x32_bf16 v[52:55], v[242:245], v[234:237], v[52:55]
	v_mfma_f32_16x16x32_bf16 v[48:51], v[242:245], v[238:241], v[48:51]
	s_waitcnt vmcnt(14)
	ds_write_b128 v130, v[76:79] offset:49152
	ds_write_b128 v130, v[80:83] offset:53248
	s_waitcnt lgkmcnt(4)
	v_mfma_f32_16x16x32_bf16 v[44:47], v[164:167], v[226:229], v[44:47]
	v_mfma_f32_16x16x32_bf16 v[40:43], v[164:167], v[230:233], v[40:43]
	v_mfma_f32_16x16x32_bf16 v[36:39], v[164:167], v[234:237], v[36:39]
	v_mfma_f32_16x16x32_bf16 v[32:35], v[164:167], v[238:241], v[32:35]
	s_waitcnt vmcnt(11)
	ds_write_b128 v130, v[88:91] offset:57344
	ds_write_b128 v130, v[72:75] offset:32768
	s_waitcnt lgkmcnt(5)
	v_mfma_f32_16x16x32_bf16 v[28:31], v[198:201], v[226:229], v[28:31]
	v_mfma_f32_16x16x32_bf16 v[24:27], v[198:201], v[230:233], v[24:27]
	v_mfma_f32_16x16x32_bf16 v[20:23], v[198:201], v[234:237], v[20:23]
	v_mfma_f32_16x16x32_bf16 v[16:19], v[198:201], v[238:241], v[16:19]
	s_waitcnt vmcnt(9)
	ds_write_b128 v130, v[96:99] offset:36864
	ds_write_b128 v130, v[100:103] offset:40960
	s_waitcnt lgkmcnt(6)
	v_mfma_f32_16x16x32_bf16 v[12:15], v[202:205], v[226:229], v[12:15]
	v_mfma_f32_16x16x32_bf16 v[8:11], v[202:205], v[230:233], v[8:11]
	v_mfma_f32_16x16x32_bf16 v[4:7], v[202:205], v[234:237], v[4:7]
	v_mfma_f32_16x16x32_bf16 v[0:3], v[202:205], v[238:241], v[0:3]
	s_waitcnt vmcnt(8)
	ds_write_b128 v130, v[108:111] offset:45056
	ds_write_b128 v130, v[92:95] offset:61440
	s_setprio 0
	s_waitcnt lgkmcnt(0)
	s_barrier
; #define GLOAD(ra, rb, koff)                                                        \
;   {                                                                                \
;     _Pragma("unroll") for (int j = 0; j < 4; j++) ra[j] = *(const u32x4*)(pa + j * sa32 + (koff));   \
;     _Pragma("unroll") for (int j = 0; j < NB_; j++) rb[j] = *(const u32x4*)(pbv[j] + (koff));         \
;   }
; template <int NT, bool PRE> ...
;     ...
;     LSTORE(ra1, rb1, 1);
;     __syncthreads();
;     GLOAD(ra1, rb1, min(k0 + 192, K - 64));
;     __builtin_amdgcn_sched_barrier(0);
;     COMPUTE(1);
; template <int NT>
; __device__ __forceinline__ void zgemm_tile(char* ws, int m0, int n0, u16* sA, u16* sB, int tq) {
;     ...
; #pragma unroll
;     for (int ni = 0; ni < NT; ni++) {
;       int col = GEMM_COL(ni, NT * 32);
;       int cb = col & ~15;
; #pragma unroll
;       for (int mi = 0; mi < 4; mi++) {
;         int row = GEMM_ROW(mi);
;         int b = row >= NPB ? 1 : 0;
;         int n = row - b * NPB;
;         f32x4 v = acc[mi][ni];
;         if (cb < 2480) *(uint2*)(Z + (size_t)row * ZLD + col) = pack4(v);
	s_min_u32 s4, s1, 0x300
	s_lshl_b32 s54, s4, 1
	ds_read_b128 v[164:167], v160 offset:32768
	ds_read_b128 v[210:213], v161 offset:49152
	ds_read_b128 v[214:217], v161 offset:51200
	ds_read_b128 v[218:221], v161 offset:53248
	ds_read_b128 v[222:225], v161 offset:55296
	ds_read_b128 v[198:201], v160 offset:34816
	ds_read_b128 v[202:205], v160 offset:36864
	ds_read_b128 v[206:209], v160 offset:38912
	ds_read_b128 v[226:229], v162 offset:32768
	ds_read_b128 v[230:233], v162 offset:34816
	ds_read_b128 v[234:237], v162 offset:36864
	ds_read_b128 v[238:241], v162 offset:38912
	ds_read_b128 v[242:245], v163 offset:49152
	v_lshl_add_u64 v[72:73], v[152:153], 0, s[54:55]
	v_add_co_u32_e32 v96, vcc, s33, v72
	v_lshl_add_u64 v[74:75], v[144:145], 0, s[54:55]
	s_nop 0
	v_addc_co_u32_e32 v97, vcc, 0, v73, vcc
	v_add_co_u32_e32 v100, vcc, s56, v72
	v_lshl_add_u64 v[80:81], v[146:147], 0, s[54:55]
	s_nop 0
	v_addc_co_u32_e32 v101, vcc, 0, v73, vcc
	v_add_co_u32_e32 v108, vcc, s57, v72
	v_lshl_add_u64 v[88:89], v[148:149], 0, s[54:55]
	v_lshl_add_u64 v[92:93], v[150:151], 0, s[54:55]
	v_addc_co_u32_e32 v109, vcc, 0, v73, vcc
	s_setprio 1
	s_waitcnt lgkmcnt(11)
	v_mfma_f32_16x16x32_bf16 v[60:63], v[210:213], v[164:167], v[60:63]
	s_waitcnt lgkmcnt(10)
	v_mfma_f32_16x16x32_bf16 v[44:47], v[214:217], v[164:167], v[44:47]
	s_waitcnt lgkmcnt(9)
	v_mfma_f32_16x16x32_bf16 v[28:31], v[218:221], v[164:167], v[28:31]
	s_waitcnt lgkmcnt(8)
	v_mfma_f32_16x16x32_bf16 v[12:15], v[222:225], v[164:167], v[12:15]
	ds_read_b128 v[164:167], v163 offset:51200
	global_load_dwordx4 v[76:79], v[74:75], off offset:384
	s_nop 0
	global_load_dwordx4 v[80:83], v[80:81], off offset:384
	s_waitcnt lgkmcnt(8)
	v_mfma_f32_16x16x32_bf16 v[56:59], v[210:213], v[198:201], v[56:59]
	v_mfma_f32_16x16x32_bf16 v[40:43], v[214:217], v[198:201], v[40:43]
	v_mfma_f32_16x16x32_bf16 v[24:27], v[218:221], v[198:201], v[24:27]
	v_mfma_f32_16x16x32_bf16 v[8:11], v[222:225], v[198:201], v[8:11]
	ds_read_b128 v[198:201], v163 offset:53248
	global_load_dwordx4 v[88:91], v[88:89], off offset:384
	s_nop 0
	global_load_dwordx4 v[92:95], v[92:93], off offset:384
	s_waitcnt lgkmcnt(8)
	v_mfma_f32_16x16x32_bf16 v[52:55], v[210:213], v[202:205], v[52:55]
	v_mfma_f32_16x16x32_bf16 v[36:39], v[214:217], v[202:205], v[36:39]
	v_mfma_f32_16x16x32_bf16 v[20:23], v[218:221], v[202:205], v[20:23]
	v_mfma_f32_16x16x32_bf16 v[4:7], v[222:225], v[202:205], v[4:7]
	ds_read_b128 v[202:205], v163 offset:55296
	global_load_dwordx4 v[72:75], v[72:73], off offset:384
	s_nop 0
	global_load_dwordx4 v[96:99], v[96:97], off offset:384
	s_waitcnt lgkmcnt(8)
	v_mfma_f32_16x16x32_bf16 v[48:51], v[210:213], v[206:209], v[48:51]
	v_mfma_f32_16x16x32_bf16 v[32:35], v[214:217], v[206:209], v[32:35]
	v_mfma_f32_16x16x32_bf16 v[16:19], v[218:221], v[206:209], v[16:19]
	v_mfma_f32_16x16x32_bf16 v[0:3], v[222:225], v[206:209], v[0:3]
	global_load_dwordx4 v[100:103], v[100:101], off offset:384
	s_nop 0
	global_load_dwordx4 v[108:111], v[108:109], off offset:384
	s_waitcnt lgkmcnt(3)
	v_mfma_f32_16x16x32_bf16 v[60:63], v[242:245], v[226:229], v[60:63]
	v_mfma_f32_16x16x32_bf16 v[56:59], v[242:245], v[230:233], v[56:59]
	v_mfma_f32_16x16x32_bf16 v[52:55], v[242:245], v[234:237], v[52:55]
	v_mfma_f32_16x16x32_bf16 v[48:51], v[242:245], v[238:241], v[48:51]
	s_waitcnt vmcnt(14)
	ds_write_b128 v130, v[104:107] offset:16384
	ds_write_b128 v130, v[84:87] offset:20480
	s_waitcnt lgkmcnt(4)
	v_mfma_f32_16x16x32_bf16 v[44:47], v[164:167], v[226:229], v[44:47]
	v_mfma_f32_16x16x32_bf16 v[40:43], v[164:167], v[230:233], v[40:43]
	v_mfma_f32_16x16x32_bf16 v[36:39], v[164:167], v[234:237], v[36:39]
	v_mfma_f32_16x16x32_bf16 v[32:35], v[164:167], v[238:241], v[32:35]
	s_waitcnt vmcnt(12)
	ds_write_b128 v130, v[64:67] offset:24576
	ds_write_b128 v130, v[68:71] offset:28672
	s_waitcnt lgkmcnt(5)
	v_mfma_f32_16x16x32_bf16 v[28:31], v[198:201], v[226:229], v[28:31]
	v_mfma_f32_16x16x32_bf16 v[24:27], v[198:201], v[230:233], v[24:27]
	v_mfma_f32_16x16x32_bf16 v[20:23], v[198:201], v[234:237], v[20:23]
	v_mfma_f32_16x16x32_bf16 v[16:19], v[198:201], v[238:241], v[16:19]
	s_waitcnt vmcnt(10)
	ds_write_b128 v130, v[124:127]
	ds_write_b128 v130, v[120:123] offset:4096
	s_waitcnt lgkmcnt(6)
	v_mfma_f32_16x16x32_bf16 v[12:15], v[202:205], v[226:229], v[12:15]
	v_mfma_f32_16x16x32_bf16 v[8:11], v[202:205], v[230:233], v[8:11]
	v_mfma_f32_16x16x32_bf16 v[4:7], v[202:205], v[234:237], v[4:7]
	v_mfma_f32_16x16x32_bf16 v[0:3], v[202:205], v[238:241], v[0:3]
	s_waitcnt vmcnt(8)
	ds_write_b128 v130, v[112:115] offset:8192
	ds_write_b128 v130, v[116:119] offset:12288
	s_setprio 0
	s_waitcnt lgkmcnt(0)
	s_barrier
	s_cmpk_lt_u32 s1, 0x380
	s_cbranch_scc1 .LBB0_231
	s_waitcnt vmcnt(13)
	v_or_b32_e32 v65, s0, v159
	v_or_b32_e32 v130, v65, v156
	v_or_b32_e32 v64, s3, v154
	s_movk_i32 s0, 0x9b0
	v_ashrrev_i32_e32 v67, 31, v130
	v_mov_b32_e32 v66, v130
	v_add_u32_e32 v64, v64, v158
	v_cmp_gt_i32_e64 s[50:51], s0, v65
	s_waitcnt vmcnt(12)
	v_lshl_add_u64 v[70:71], v[66:67], 1, s[18:19]
	s_and_saveexec_b64 s[0:1], s[50:51]
	s_cbranch_execz .LBB0_234
	v_cvt_pk_bf16_f32 v66, v60, v61
	v_cvt_pk_bf16_f32 v67, v62, v63
	v_mad_i64_i32 v[68:69], s[4:5], v64, s91, v[70:71]
	global_store_dwordx2 v[68:69], v[66:67], off

; #define GLOAD(ra, rb, koff)                                                        \
;   {                                                                                \
;     _Pragma("unroll") for (int j = 0; j < 4; j++) ra[j] = *(const u32x4*)(pa + j * sa32 + (koff));   \
;     _Pragma("unroll") for (int j = 0; j < NB_; j++) rb[j] = *(const u32x4*)(pbv[j] + (koff));         \
;   }
; template <int NT, bool PRE> ...
;     ...
;   if (!PRE) {
;     GLOAD(ra0, rb0, 0);
;     GLOAD(ra1, rb1, 64);
;   }
;   __syncthreads();
;   for (int k0 = 0; k0 < K; k0 += 128) {
;     LSTORE(ra0, rb0, 0);
; __device__ __forceinline__ void phase_merge(const Params& P, u16* sA, u16* sB) {
;     ...
;   for (int t = blockIdx.x; t < 132 * 32; t += gridDim.x) {
;     const int m0 = (t % 132) * 128, n0 = (t / 132) * 32;
;     u32x2 gp[4][4];
;     {
;       f32x4 ag[4][4];
;       zero_acc<4>(ag);
;       const u16* pa = Hb + (size_t)(m0 + (tq >> 3)) * 1024 + (tq & 7) * 8;
;       const u16* pbv[4];
; #pragma unroll
;       for (int j = 0; j < 4; j++) {
;         int ni = (tq >> 7) + 2 * (j & 1);
;         int grow = ni * 1024 + n0 + (j >> 1) * 16 + ((tq >> 3) & 15);
;         pbv[j] = (const u16*)(ws + O_WG) + (size_t)grow * 1024 + (tq & 7) * 8;
;       }
;       gemm_core<4>(pa, (size_t)32 * 1024, pbv, 1024, ag, sA, sB, tq);
.LBB0_1988:
	s_cmp_lg_u32 s90, 0x200
	s_cbranch_scc1 .Lrm_mg_orig
	s_cmp_ge_u32 s18, 4096
	s_cbranch_scc1 .Lrm_mg_orig
	s_and_b32 s21, s18, 7
	s_lshl_b32 s21, s21, 6
	s_bfe_u32 s20, s18, 0x60003
	s_or_b32 s21, s21, s20
	s_andn2_b32 s20, s18, 0x1ff
	s_or_b32 s21, s21, s20
	s_cmp_lt_u32 s21, 3168
	s_cbranch_scc0 .Lrm_mg_b
	s_lshr_b32 s20, s21, 3
	s_mul_hi_u32 s20, s20, 0x3e0f83e1
	s_lshr_b32 s20, s20, 5
	s_mul_i32 s19, s20, 1056
	s_sub_i32 s21, s21, s19
	s_lshl_b32 s20, s20, 3
	s_and_b32 s19, s21, 7
	s_add_i32 s20, s20, s19
	s_lshr_b32 s19, s21, 3
	s_branch .Lrm_mg_done
.Lrm_mg_b:
	s_sub_i32 s21, s21, 3168
	s_cmp_lt_u32 s21, 924
	s_cbranch_scc0 .Lrm_mg_c
	s_mul_i32 s19, s21, 9363
	s_lshr_b32 s19, s19, 16
	s_mul_i32 s20, s19, 7
	s_sub_i32 s20, s21, s20
	s_add_i32 s20, s20, 24
	s_branch .Lrm_mg_done
.Lrm_mg_c:
	s_sub_i32 s19, s21, 924
	s_movk_i32 s20, 31
	s_branch .Lrm_mg_done
.Lrm_mg_orig:
	s_mul_hi_u32 s20, s18, 0x3e0f83e1
	s_lshr_b32 s20, s20, 5
	s_mul_i32 s21, s20, 0x84
	s_sub_i32 s19, s18, s21
.Lrm_mg_done:
	s_lshl_b32 s20, s20, 5
	v_add_u32_e32 v4, s20, v151
	v_or_b32_e32 v2, v4, v147
	v_ashrrev_i32_e32 v3, 31, v2
	v_lshlrev_b64 v[2:3], 11, v[2:3]
	v_add_u32_e32 v5, 0x800, v4
	v_lshl_add_u64 v[136:137], v[134:135], 0, v[2:3]
	v_or_b32_e32 v2, v5, v147
	v_ashrrev_i32_e32 v3, 31, v2
	s_lshl_b32 s19, s19, 7
	v_lshlrev_b64 v[2:3], 11, v[2:3]
	v_add_u32_e32 v0, s19, v146
	v_lshl_add_u64 v[138:139], v[134:135], 0, v[2:3]
	v_or_b32_e32 v2, v4, v152
	v_ashrrev_i32_e32 v1, 31, v0
	v_ashrrev_i32_e32 v3, 31, v2
	v_lshlrev_b64 v[0:1], 11, v[0:1]
	v_lshlrev_b64 v[2:3], 11, v[2:3]
	v_lshl_add_u64 v[140:141], v[134:135], 0, v[2:3]
	v_or_b32_e32 v2, v5, v152
	v_lshl_add_u64 v[144:145], v[132:133], 0, v[0:1]
	v_ashrrev_i32_e32 v3, 31, v2
	v_add_co_u32_e32 v0, vcc, s33, v144
	v_lshlrev_b64 v[2:3], 11, v[2:3]
	s_nop 0
	v_addc_co_u32_e32 v1, vcc, 0, v145, vcc
	v_lshl_add_u64 v[142:143], v[134:135], 0, v[2:3]
	v_add_co_u32_e32 v2, vcc, s56, v144
	s_movk_i32 s21, 0xff80
	s_nop 0
	v_addc_co_u32_e32 v3, vcc, 0, v145, vcc
	v_add_co_u32_e32 v4, vcc, s57, v144
	s_nop 1
	v_addc_co_u32_e32 v5, vcc, 0, v145, vcc
	global_load_dwordx4 v[108:111], v[144:145], off
	global_load_dwordx4 v[60:63], v[144:145], off offset:128
	global_load_dwordx4 v[120:123], v[0:1], off
	global_load_dwordx4 v[80:83], v[0:1], off offset:128
	global_load_dwordx4 v[112:115], v[2:3], off
	global_load_dwordx4 v[96:99], v[2:3], off offset:128
	global_load_dwordx4 v[116:119], v[4:5], off
	global_load_dwordx4 v[104:107], v[4:5], off offset:128
	global_load_dwordx4 v[100:103], v[136:137], off
	global_load_dwordx4 v[64:67], v[136:137], off offset:128
	global_load_dwordx4 v[84:87], v[138:139], off
	global_load_dwordx4 v[68:71], v[138:139], off offset:128
	global_load_dwordx4 v[72:75], v[140:141], off
	global_load_dwordx4 v[76:79], v[140:141], off offset:128
	global_load_dwordx4 v[92:95], v[142:143], off
	global_load_dwordx4 v[88:91], v[142:143], off offset:128
	v_mov_b32_e32 v0, 0
	v_mov_b32_e32 v1, v0
	v_mov_b32_e32 v2, v0
	v_mov_b32_e32 v3, v0
	v_mov_b32_e32 v4, v0
	v_mov_b32_e32 v5, v0
	v_mov_b32_e32 v6, v0
	v_mov_b32_e32 v7, v0
	v_mov_b32_e32 v8, v0
	v_mov_b32_e32 v9, v0
	v_mov_b32_e32 v10, v0
	v_mov_b32_e32 v11, v0
	v_mov_b32_e32 v12, v0
	v_mov_b32_e32 v13, v0
	v_mov_b32_e32 v14, v0
	v_mov_b32_e32 v15, v0
	v_mov_b32_e32 v16, v0
	v_mov_b32_e32 v17, v0
	v_mov_b32_e32 v18, v0
	v_mov_b32_e32 v19, v0
	v_mov_b32_e32 v20, v0
	v_mov_b32_e32 v21, v0
	v_mov_b32_e32 v22, v0
	v_mov_b32_e32 v23, v0
	v_mov_b32_e32 v24, v0
	v_mov_b32_e32 v25, v0
	v_mov_b32_e32 v26, v0
	v_mov_b32_e32 v27, v0
	s_waitcnt vmcnt(17)
	v_mov_b32_e32 v28, v0
	v_mov_b32_e32 v29, v0
	v_mov_b32_e32 v30, v0
	v_mov_b32_e32 v31, v0
	v_mov_b32_e32 v32, v0
	v_mov_b32_e32 v33, v0
	v_mov_b32_e32 v34, v0
	v_mov_b32_e32 v35, v0
	v_mov_b32_e32 v36, v0
	v_mov_b32_e32 v37, v0
	v_mov_b32_e32 v38, v0
	v_mov_b32_e32 v39, v0
	v_mov_b32_e32 v40, v0
	v_mov_b32_e32 v41, v0
	v_mov_b32_e32 v42, v0
	v_mov_b32_e32 v43, v0
	s_waitcnt vmcnt(16)
	v_mov_b32_e32 v44, v0
	v_mov_b32_e32 v45, v0
	v_mov_b32_e32 v46, v0
	v_mov_b32_e32 v47, v0
	v_mov_b32_e32 v48, v0
	v_mov_b32_e32 v49, v0
	v_mov_b32_e32 v50, v0
	v_mov_b32_e32 v51, v0
	v_mov_b32_e32 v52, v0
	v_mov_b32_e32 v53, v0
	v_mov_b32_e32 v54, v0
	v_mov_b32_e32 v55, v0
	v_mov_b32_e32 v56, v0
	v_mov_b32_e32 v57, v0
	v_mov_b32_e32 v58, v0
	v_mov_b32_e32 v59, v0
	v_mov_b32_e32 v124, v0
	v_mov_b32_e32 v125, v0
	v_mov_b32_e32 v126, v0
	v_mov_b32_e32 v127, v0
	s_barrier
	s_waitcnt vmcnt(11)
	ds_write_b128 v148, v[108:111]
	s_waitcnt vmcnt(10)
	ds_write_b128 v148, v[120:123] offset:4096
	s_waitcnt vmcnt(9)
	ds_write_b128 v148, v[112:115] offset:8192
	s_waitcnt vmcnt(8)
	ds_write_b128 v148, v[116:119] offset:12288
	s_waitcnt vmcnt(7)
	ds_write_b128 v148, v[100:103] offset:16384
	s_waitcnt vmcnt(5)
	ds_write_b128 v148, v[84:87] offset:20480
	s_waitcnt vmcnt(3)
	ds_write_b128 v148, v[72:75] offset:24576
	s_waitcnt vmcnt(1)
	ds_write_b128 v148, v[92:95] offset:28672
	s_waitcnt lgkmcnt(0)
	s_barrier
; #define GLOAD(ra, rb, koff)                                                        \
;   {                                                                                \
;     _Pragma("unroll") for (int j = 0; j < 4; j++) ra[j] = *(const u32x4*)(pa + j * sa32 + (koff));   \
;     _Pragma("unroll") for (int j = 0; j < NB_; j++) rb[j] = *(const u32x4*)(pbv[j] + (koff));         \
;   }
; template <int NT, bool PRE> ...
;     ...
;   const int wsw = ((tid & 7) ^ ((tid >> 4) & 7)) * 8;
;   const int rsw = (lane & 15) >> 1;
;     ...
;   if (!PRE) {
;     GLOAD(ra0, rb0, 0);
;     GLOAD(ra1, rb1, 64);
;   }
;   __syncthreads();
;   for (int k0 = 0; k0 < K; k0 += 128) {
;     LSTORE(ra0, rb0, 0);
;     __syncthreads();
;     GLOAD(ra0, rb0, min(k0 + 128, K - 128));
;     __builtin_amdgcn_sched_barrier(0);
;     COMPUTE(0);
.LBB0_1989:
	s_add_i32 s22, s21, 0x100
	s_min_u32 s22, s22, 0x380
	s_lshl_b32 s54, s22, 1
	ds_read_b128 v[158:161], v153
	ds_read_b128 v[206:209], v154 offset:16384
	ds_read_b128 v[210:213], v154 offset:18432
	ds_read_b128 v[214:217], v154 offset:20480
	ds_read_b128 v[218:221], v154 offset:22528
	ds_read_b128 v[162:165], v153 offset:2048
	ds_read_b128 v[198:201], v153 offset:4096
	ds_read_b128 v[202:205], v153 offset:6144
	ds_read_b128 v[222:225], v155
	ds_read_b128 v[226:229], v155 offset:2048
	ds_read_b128 v[230:233], v155 offset:4096
	ds_read_b128 v[234:237], v155 offset:6144
	ds_read_b128 v[238:241], v156 offset:16384
	ds_read_b128 v[242:245], v156 offset:18432
	v_lshl_add_u64 v[108:109], v[144:145], 0, s[54:55]
	v_add_co_u32_e32 v112, vcc, s33, v108
	v_lshl_add_u64 v[72:73], v[136:137], 0, s[54:55]
	s_nop 0
	v_addc_co_u32_e32 v113, vcc, 0, v109, vcc
	v_add_co_u32_e32 v114, vcc, s56, v108
	v_lshl_add_u64 v[74:75], v[138:139], 0, s[54:55]
	s_nop 0
	v_addc_co_u32_e32 v115, vcc, 0, v109, vcc
	v_add_co_u32_e32 v116, vcc, s57, v108
	v_lshl_add_u64 v[92:93], v[140:141], 0, s[54:55]
	v_lshl_add_u64 v[94:95], v[142:143], 0, s[54:55]
	v_addc_co_u32_e32 v117, vcc, 0, v109, vcc
	s_addk_i32 s21, 0x80
	s_setprio 1
	s_waitcnt lgkmcnt(12)
	v_mfma_f32_16x16x32_bf16 v[124:127], v[206:209], v[158:161], v[124:127]
	s_waitcnt lgkmcnt(11)
	v_mfma_f32_16x16x32_bf16 v[56:59], v[210:213], v[158:161], v[56:59]
	s_waitcnt lgkmcnt(10)
	v_mfma_f32_16x16x32_bf16 v[52:55], v[214:217], v[158:161], v[52:55]
	s_waitcnt lgkmcnt(9)
	v_mfma_f32_16x16x32_bf16 v[48:51], v[218:221], v[158:161], v[48:51]
	ds_read_b128 v[158:161], v156 offset:20480
	global_load_dwordx4 v[100:103], v[72:73], off
	s_nop 0
	global_load_dwordx4 v[84:87], v[74:75], off
	s_waitcnt lgkmcnt(9)
	v_mfma_f32_16x16x32_bf16 v[44:47], v[206:209], v[162:165], v[44:47]
	v_mfma_f32_16x16x32_bf16 v[40:43], v[210:213], v[162:165], v[40:43]
	v_mfma_f32_16x16x32_bf16 v[36:39], v[214:217], v[162:165], v[36:39]
	v_mfma_f32_16x16x32_bf16 v[32:35], v[218:221], v[162:165], v[32:35]
	ds_read_b128 v[162:165], v156 offset:22528
	global_load_dwordx4 v[72:75], v[92:93], off
	s_nop 0
	global_load_dwordx4 v[92:95], v[94:95], off
	s_waitcnt lgkmcnt(9)
	v_mfma_f32_16x16x32_bf16 v[28:31], v[206:209], v[198:201], v[28:31]
	v_mfma_f32_16x16x32_bf16 v[24:27], v[210:213], v[198:201], v[24:27]
	v_mfma_f32_16x16x32_bf16 v[20:23], v[214:217], v[198:201], v[20:23]
	v_mfma_f32_16x16x32_bf16 v[16:19], v[218:221], v[198:201], v[16:19]
	global_load_dwordx4 v[108:111], v[108:109], off
	s_nop 0
	global_load_dwordx4 v[120:123], v[112:113], off
	s_waitcnt lgkmcnt(8)
	v_mfma_f32_16x16x32_bf16 v[12:15], v[206:209], v[202:205], v[12:15]
	v_mfma_f32_16x16x32_bf16 v[8:11], v[210:213], v[202:205], v[8:11]
	v_mfma_f32_16x16x32_bf16 v[4:7], v[214:217], v[202:205], v[4:7]
	v_mfma_f32_16x16x32_bf16 v[0:3], v[218:221], v[202:205], v[0:3]
	global_load_dwordx4 v[112:115], v[114:115], off
	s_nop 0
	global_load_dwordx4 v[116:119], v[116:117], off
	s_waitcnt lgkmcnt(3)
	v_mfma_f32_16x16x32_bf16 v[124:127], v[238:241], v[222:225], v[124:127]
	v_mfma_f32_16x16x32_bf16 v[44:47], v[238:241], v[226:229], v[44:47]
	v_mfma_f32_16x16x32_bf16 v[28:31], v[238:241], v[230:233], v[28:31]
	v_mfma_f32_16x16x32_bf16 v[12:15], v[238:241], v[234:237], v[12:15]
	s_waitcnt vmcnt(14)
	ds_write_b128 v148, v[64:67] offset:49152
	ds_write_b128 v148, v[68:71] offset:53248
	s_waitcnt lgkmcnt(4)
	v_mfma_f32_16x16x32_bf16 v[56:59], v[242:245], v[222:225], v[56:59]
	v_mfma_f32_16x16x32_bf16 v[40:43], v[242:245], v[226:229], v[40:43]
	v_mfma_f32_16x16x32_bf16 v[24:27], v[242:245], v[230:233], v[24:27]
	v_mfma_f32_16x16x32_bf16 v[8:11], v[242:245], v[234:237], v[8:11]
	s_waitcnt vmcnt(11)
	ds_write_b128 v148, v[76:79] offset:57344
	ds_write_b128 v148, v[60:63] offset:32768
	s_waitcnt lgkmcnt(5)
	v_mfma_f32_16x16x32_bf16 v[52:55], v[158:161], v[222:225], v[52:55]
	v_mfma_f32_16x16x32_bf16 v[36:39], v[158:161], v[226:229], v[36:39]
	v_mfma_f32_16x16x32_bf16 v[20:23], v[158:161], v[230:233], v[20:23]
	v_mfma_f32_16x16x32_bf16 v[4:7], v[158:161], v[234:237], v[4:7]
	s_waitcnt vmcnt(9)
	ds_write_b128 v148, v[80:83] offset:36864
	ds_write_b128 v148, v[96:99] offset:40960
	s_waitcnt lgkmcnt(6)
	v_mfma_f32_16x16x32_bf16 v[48:51], v[162:165], v[222:225], v[48:51]
	v_mfma_f32_16x16x32_bf16 v[32:35], v[162:165], v[226:229], v[32:35]
	v_mfma_f32_16x16x32_bf16 v[16:19], v[162:165], v[230:233], v[16:19]
	v_mfma_f32_16x16x32_bf16 v[0:3], v[162:165], v[234:237], v[0:3]
	s_waitcnt vmcnt(8)
	ds_write_b128 v148, v[104:107] offset:45056
	ds_write_b128 v148, v[88:91] offset:61440
	s_setprio 0
	s_waitcnt lgkmcnt(0)
	s_barrier
; #define GLOAD(ra, rb, koff)                                                        \
;   {                                                                                \
;     _Pragma("unroll") for (int j = 0; j < 4; j++) ra[j] = *(const u32x4*)(pa + j * sa32 + (koff));   \
;     _Pragma("unroll") for (int j = 0; j < NB_; j++) rb[j] = *(const u32x4*)(pbv[j] + (koff));         \
;   }
; template <int NT, bool PRE> ...
;     ...
;   if (!PRE) {
;     GLOAD(ra0, rb0, 0);
;     GLOAD(ra1, rb1, 64);
;   }
;   __syncthreads();
;   for (int k0 = 0; k0 < K; k0 += 128) {
;     LSTORE(ra0, rb0, 0);
;     __syncthreads();
;     GLOAD(ra0, rb0, min(k0 + 128, K - 128));
;     __builtin_amdgcn_sched_barrier(0);
;     COMPUTE(0);
;     LSTORE(ra1, rb1, 1);
;     __syncthreads();
;     GLOAD(ra1, rb1, min(k0 + 192, K - 64));
;     __builtin_amdgcn_sched_barrier(0);
;     COMPUTE(1);
	s_min_u32 s22, s21, 0x300
	s_lshl_b32 s54, s22, 1
	ds_read_b128 v[158:161], v153 offset:32768
	ds_read_b128 v[206:209], v154 offset:49152
	ds_read_b128 v[210:213], v154 offset:51200
	ds_read_b128 v[214:217], v154 offset:53248
	ds_read_b128 v[218:221], v154 offset:55296
	ds_read_b128 v[162:165], v153 offset:34816
	ds_read_b128 v[198:201], v153 offset:36864
	ds_read_b128 v[202:205], v153 offset:38912
	ds_read_b128 v[222:225], v155 offset:32768
	ds_read_b128 v[226:229], v155 offset:34816
	ds_read_b128 v[230:233], v155 offset:36864
	ds_read_b128 v[234:237], v155 offset:38912
	ds_read_b128 v[238:241], v156 offset:49152
	ds_read_b128 v[242:245], v156 offset:51200
	v_lshl_add_u64 v[60:61], v[144:145], 0, s[54:55]
	v_add_co_u32_e32 v82, vcc, s33, v60
	v_lshl_add_u64 v[62:63], v[136:137], 0, s[54:55]
	s_nop 0
	v_addc_co_u32_e32 v83, vcc, 0, v61, vcc
	v_add_co_u32_e32 v96, vcc, s56, v60
	v_lshl_add_u64 v[68:69], v[138:139], 0, s[54:55]
	s_nop 0
	v_addc_co_u32_e32 v97, vcc, 0, v61, vcc
	v_add_co_u32_e32 v104, vcc, s57, v60
	v_lshl_add_u64 v[76:77], v[140:141], 0, s[54:55]
	v_lshl_add_u64 v[80:81], v[142:143], 0, s[54:55]
	v_addc_co_u32_e32 v105, vcc, 0, v61, vcc
	s_setprio 1
	s_waitcnt lgkmcnt(12)
	v_mfma_f32_16x16x32_bf16 v[124:127], v[206:209], v[158:161], v[124:127]
	s_waitcnt lgkmcnt(11)
	v_mfma_f32_16x16x32_bf16 v[56:59], v[210:213], v[158:161], v[56:59]
	s_waitcnt lgkmcnt(10)
	v_mfma_f32_16x16x32_bf16 v[52:55], v[214:217], v[158:161], v[52:55]
	s_waitcnt lgkmcnt(9)
	v_mfma_f32_16x16x32_bf16 v[48:51], v[218:221], v[158:161], v[48:51]
	ds_read_b128 v[158:161], v156 offset:53248
	global_load_dwordx4 v[64:67], v[62:63], off offset:384
	s_nop 0
	global_load_dwordx4 v[68:71], v[68:69], off offset:384
	s_waitcnt lgkmcnt(9)
	v_mfma_f32_16x16x32_bf16 v[44:47], v[206:209], v[162:165], v[44:47]
	v_mfma_f32_16x16x32_bf16 v[40:43], v[210:213], v[162:165], v[40:43]
	v_mfma_f32_16x16x32_bf16 v[36:39], v[214:217], v[162:165], v[36:39]
	v_mfma_f32_16x16x32_bf16 v[32:35], v[218:221], v[162:165], v[32:35]
	ds_read_b128 v[162:165], v156 offset:55296
	global_load_dwordx4 v[76:79], v[76:77], off offset:384
	s_nop 0
	global_load_dwordx4 v[88:91], v[80:81], off offset:384
	s_waitcnt lgkmcnt(9)
	v_mfma_f32_16x16x32_bf16 v[28:31], v[206:209], v[198:201], v[28:31]
	v_mfma_f32_16x16x32_bf16 v[24:27], v[210:213], v[198:201], v[24:27]
	v_mfma_f32_16x16x32_bf16 v[20:23], v[214:217], v[198:201], v[20:23]
	v_mfma_f32_16x16x32_bf16 v[16:19], v[218:221], v[198:201], v[16:19]
	global_load_dwordx4 v[60:63], v[60:61], off offset:384
	s_nop 0
	global_load_dwordx4 v[80:83], v[82:83], off offset:384
	s_waitcnt lgkmcnt(8)
	v_mfma_f32_16x16x32_bf16 v[12:15], v[206:209], v[202:205], v[12:15]
	v_mfma_f32_16x16x32_bf16 v[8:11], v[210:213], v[202:205], v[8:11]
	v_mfma_f32_16x16x32_bf16 v[4:7], v[214:217], v[202:205], v[4:7]
	v_mfma_f32_16x16x32_bf16 v[0:3], v[218:221], v[202:205], v[0:3]
	global_load_dwordx4 v[96:99], v[96:97], off offset:384
	s_nop 0
	global_load_dwordx4 v[104:107], v[104:105], off offset:384
	s_waitcnt lgkmcnt(3)
	v_mfma_f32_16x16x32_bf16 v[124:127], v[238:241], v[222:225], v[124:127]
	v_mfma_f32_16x16x32_bf16 v[44:47], v[238:241], v[226:229], v[44:47]
	v_mfma_f32_16x16x32_bf16 v[28:31], v[238:241], v[230:233], v[28:31]
	v_mfma_f32_16x16x32_bf16 v[12:15], v[238:241], v[234:237], v[12:15]
	s_waitcnt vmcnt(14)
	ds_write_b128 v148, v[100:103] offset:16384
	ds_write_b128 v148, v[84:87] offset:20480
	s_waitcnt lgkmcnt(4)
	v_mfma_f32_16x16x32_bf16 v[56:59], v[242:245], v[222:225], v[56:59]
	v_mfma_f32_16x16x32_bf16 v[40:43], v[242:245], v[226:229], v[40:43]
	v_mfma_f32_16x16x32_bf16 v[24:27], v[242:245], v[230:233], v[24:27]
	v_mfma_f32_16x16x32_bf16 v[8:11], v[242:245], v[234:237], v[8:11]
	s_waitcnt vmcnt(12)
	ds_write_b128 v148, v[72:75] offset:24576
	ds_write_b128 v148, v[92:95] offset:28672
	s_waitcnt lgkmcnt(5)
	v_mfma_f32_16x16x32_bf16 v[52:55], v[158:161], v[222:225], v[52:55]
	v_mfma_f32_16x16x32_bf16 v[36:39], v[158:161], v[226:229], v[36:39]
	v_mfma_f32_16x16x32_bf16 v[20:23], v[158:161], v[230:233], v[20:23]
	v_mfma_f32_16x16x32_bf16 v[4:7], v[158:161], v[234:237], v[4:7]
	s_waitcnt vmcnt(10)
	ds_write_b128 v148, v[108:111]
	ds_write_b128 v148, v[120:123] offset:4096
	s_waitcnt lgkmcnt(6)
	v_mfma_f32_16x16x32_bf16 v[48:51], v[162:165], v[222:225], v[48:51]
	v_mfma_f32_16x16x32_bf16 v[32:35], v[162:165], v[226:229], v[32:35]
	v_mfma_f32_16x16x32_bf16 v[16:19], v[162:165], v[230:233], v[16:19]
	v_mfma_f32_16x16x32_bf16 v[0:3], v[162:165], v[234:237], v[0:3]
	s_waitcnt vmcnt(8)
	ds_write_b128 v148, v[112:115] offset:8192
	ds_write_b128 v148, v[116:119] offset:12288
	s_setprio 0
	s_waitcnt lgkmcnt(0)
	s_barrier
	s_cmpk_lt_u32 s21, 0x380
	s_cbranch_scc1 .LBB0_1989
; __device__ __forceinline__ float sigmoidf_(float x) { return 1.f / (1.f + __expf(-x)); }
; __device__ __forceinline__ void phase_merge(const Params& P, u16* sA, u16* sB) {
;     ...
; #pragma unroll
;       for (int mi = 0; mi < 4; mi++)
; #pragma unroll
;         for (int ni = 0; ni < 4; ni++) {
;           f32x4 g = ag[mi][ni];
;           gp[mi][ni] = u32x2{pk2bf(sigmoidf_(g[0]), sigmoidf_(g[1])), pk2bf(sigmoidf_(g[2]), sigmoidf_(g[3]))};
;         }
	s_waitcnt vmcnt(3)
	v_mul_f32_e32 v60, 0xbfb8aa3b, v124
	v_mul_f32_e32 v61, 0xbfb8aa3b, v125
	v_exp_f32_e32 v60, v60
	v_exp_f32_e32 v61, v61
	v_mul_f32_e32 v56, 0xbfb8aa3b, v56
	v_mul_f32_e32 v57, 0xbfb8aa3b, v57
	v_exp_f32_e32 v56, v56
	v_pk_add_f32 v[60:61], v[60:61], 1.0 op_sel_hi:[1,0]
	v_exp_f32_e32 v57, v57
	v_div_scale_f32 v62, s[22:23], v61, v61, 1.0
	v_rcp_f32_e32 v63, v62
	v_pk_add_f32 v[56:57], v[56:57], 1.0 op_sel_hi:[1,0]
	v_mul_f32_e32 v52, 0xbfb8aa3b, v52
	v_mul_f32_e32 v53, 0xbfb8aa3b, v53
	v_fma_f32 v64, -v62, v63, 1.0
	v_fmac_f32_e32 v63, v64, v63
	v_div_scale_f32 v64, vcc, 1.0, v61, 1.0
	v_mul_f32_e32 v65, v64, v63
	v_fma_f32 v66, -v62, v65, v64
	v_fmac_f32_e32 v65, v66, v63
	v_fma_f32 v62, -v62, v65, v64
	v_div_fmas_f32 v62, v62, v63, v65
	v_div_fixup_f32 v61, v62, v61, 1.0
	v_div_scale_f32 v62, s[22:23], v60, v60, 1.0
	v_rcp_f32_e32 v63, v62
	v_exp_f32_e32 v52, v52
	v_exp_f32_e32 v53, v53
	v_mul_f32_e32 v48, 0xbfb8aa3b, v48
	v_fma_f32 v64, -v62, v63, 1.0
	v_fmac_f32_e32 v63, v64, v63
	v_div_scale_f32 v64, vcc, 1.0, v60, 1.0
	v_mul_f32_e32 v65, v64, v63
	v_fma_f32 v66, -v62, v65, v64
	v_fmac_f32_e32 v65, v66, v63
	v_fma_f32 v62, -v62, v65, v64
	v_div_fmas_f32 v62, v62, v63, v65
	v_div_fixup_f32 v60, v62, v60, 1.0
	v_cvt_pk_bf16_f32 v60, v60, v61
	v_mul_f32_e32 v61, 0xbfb8aa3b, v126
	v_exp_f32_e32 v62, v61
	v_mul_f32_e32 v61, 0xbfb8aa3b, v127
	v_exp_f32_e32 v63, v61
	v_pk_add_f32 v[52:53], v[52:53], 1.0 op_sel_hi:[1,0]
	v_mul_f32_e32 v49, 0xbfb8aa3b, v49
	v_exp_f32_e32 v48, v48
	v_pk_add_f32 v[62:63], v[62:63], 1.0 op_sel_hi:[1,0]
	v_exp_f32_e32 v49, v49
	v_div_scale_f32 v61, s[22:23], v63, v63, 1.0
	v_rcp_f32_e32 v64, v61
	v_pk_add_f32 v[48:49], v[48:49], 1.0 op_sel_hi:[1,0]
	v_mul_f32_e32 v44, 0xbfb8aa3b, v44
	v_mul_f32_e32 v45, 0xbfb8aa3b, v45
	v_fma_f32 v65, -v61, v64, 1.0
	v_fmac_f32_e32 v64, v65, v64
	v_div_scale_f32 v65, vcc, 1.0, v63, 1.0
	v_mul_f32_e32 v66, v65, v64
	v_fma_f32 v67, -v61, v66, v65
	v_fmac_f32_e32 v66, v67, v64
	v_fma_f32 v61, -v61, v66, v65
	v_div_fmas_f32 v61, v61, v64, v66
	v_div_fixup_f32 v61, v61, v63, 1.0
	v_div_scale_f32 v63, s[22:23], v62, v62, 1.0
	v_rcp_f32_e32 v64, v63
	v_exp_f32_e32 v44, v44
	v_exp_f32_e32 v45, v45
	v_mul_f32_e32 v40, 0xbfb8aa3b, v40
	v_fma_f32 v65, -v63, v64, 1.0
	v_fmac_f32_e32 v64, v65, v64
	v_div_scale_f32 v65, vcc, 1.0, v62, 1.0
	v_mul_f32_e32 v66, v65, v64
	v_fma_f32 v67, -v63, v66, v65
	v_fmac_f32_e32 v66, v67, v64
	v_fma_f32 v63, -v63, v66, v65
	v_div_fmas_f32 v63, v63, v64, v66
	v_div_fixup_f32 v62, v63, v62, 1.0
	v_cvt_pk_bf16_f32 v61, v62, v61
	v_div_scale_f32 v62, s[22:23], v57, v57, 1.0
	v_rcp_f32_e32 v63, v62
	v_pk_add_f32 v[44:45], v[44:45], 1.0 op_sel_hi:[1,0]
	v_mul_f32_e32 v41, 0xbfb8aa3b, v41
	v_exp_f32_e32 v40, v40
	v_fma_f32 v64, -v62, v63, 1.0
	v_fmac_f32_e32 v63, v64, v63
	v_div_scale_f32 v64, vcc, 1.0, v57, 1.0
	v_mul_f32_e32 v65, v64, v63
	v_fma_f32 v66, -v62, v65, v64
	v_fmac_f32_e32 v65, v66, v63
	v_fma_f32 v62, -v62, v65, v64
	v_div_fmas_f32 v62, v62, v63, v65
	v_div_fixup_f32 v57, v62, v57, 1.0
	v_div_scale_f32 v62, s[22:23], v56, v56, 1.0
	v_rcp_f32_e32 v63, v62
	v_exp_f32_e32 v41, v41
	v_mul_f32_e32 v36, 0xbfb8aa3b, v36
	v_mul_f32_e32 v37, 0xbfb8aa3b, v37
	v_fma_f32 v64, -v62, v63, 1.0
	v_fmac_f32_e32 v63, v64, v63
	v_div_scale_f32 v64, vcc, 1.0, v56, 1.0
	v_mul_f32_e32 v65, v64, v63
	v_fma_f32 v66, -v62, v65, v64
	v_fmac_f32_e32 v65, v66, v63
	v_fma_f32 v62, -v62, v65, v64
	v_div_fmas_f32 v62, v62, v63, v65
	v_div_fixup_f32 v56, v62, v56, 1.0
	v_cvt_pk_bf16_f32 v56, v56, v57
	v_mul_f32_e32 v57, 0xbfb8aa3b, v58
	v_exp_f32_e32 v58, v57
	v_mul_f32_e32 v57, 0xbfb8aa3b, v59
	v_exp_f32_e32 v59, v57
	v_pk_add_f32 v[40:41], v[40:41], 1.0 op_sel_hi:[1,0]
	v_exp_f32_e32 v36, v36
	v_exp_f32_e32 v37, v37
	v_pk_add_f32 v[58:59], v[58:59], 1.0 op_sel_hi:[1,0]
	v_mul_f32_e32 v32, 0xbfb8aa3b, v32
	v_div_scale_f32 v57, s[22:23], v59, v59, 1.0
	v_rcp_f32_e32 v62, v57
	v_pk_add_f32 v[36:37], v[36:37], 1.0 op_sel_hi:[1,0]
	v_mul_f32_e32 v33, 0xbfb8aa3b, v33
	v_exp_f32_e32 v32, v32
	v_fma_f32 v63, -v57, v62, 1.0
	v_fmac_f32_e32 v62, v63, v62
	v_div_scale_f32 v63, vcc, 1.0, v59, 1.0
	v_mul_f32_e32 v64, v63, v62
	v_fma_f32 v65, -v57, v64, v63
	v_fmac_f32_e32 v64, v65, v62
	v_fma_f32 v57, -v57, v64, v63
	v_div_fmas_f32 v57, v57, v62, v64
	v_div_fixup_f32 v57, v57, v59, 1.0
	v_div_scale_f32 v59, s[22:23], v58, v58, 1.0
	v_rcp_f32_e32 v62, v59
	v_exp_f32_e32 v33, v33
	v_mul_f32_e32 v28, 0xbfb8aa3b, v28
	v_mul_f32_e32 v29, 0xbfb8aa3b, v29
	v_fma_f32 v63, -v59, v62, 1.0
	v_fmac_f32_e32 v62, v63, v62
	v_div_scale_f32 v63, vcc, 1.0, v58, 1.0
	v_mul_f32_e32 v64, v63, v62
	v_fma_f32 v65, -v59, v64, v63
	v_fmac_f32_e32 v64, v65, v62
	v_fma_f32 v59, -v59, v64, v63
	v_div_fmas_f32 v59, v59, v62, v64
	v_div_fixup_f32 v58, v59, v58, 1.0
	v_cvt_pk_bf16_f32 v57, v58, v57
	v_div_scale_f32 v58, s[22:23], v53, v53, 1.0
	v_rcp_f32_e32 v59, v58
	v_pk_add_f32 v[32:33], v[32:33], 1.0 op_sel_hi:[1,0]
	v_exp_f32_e32 v28, v28
	v_exp_f32_e32 v29, v29
	v_fma_f32 v62, -v58, v59, 1.0
	v_fmac_f32_e32 v59, v62, v59
	v_div_scale_f32 v62, vcc, 1.0, v53, 1.0
	v_mul_f32_e32 v63, v62, v59
	v_fma_f32 v64, -v58, v63, v62
	v_fmac_f32_e32 v63, v64, v59
	v_fma_f32 v58, -v58, v63, v62
	v_div_fmas_f32 v58, v58, v59, v63
	v_div_fixup_f32 v53, v58, v53, 1.0
	v_div_scale_f32 v58, s[22:23], v52, v52, 1.0
	v_rcp_f32_e32 v59, v58
	v_pk_add_f32 v[28:29], v[28:29], 1.0 op_sel_hi:[1,0]
	v_mul_f32_e32 v24, 0xbfb8aa3b, v24
	v_mul_f32_e32 v25, 0xbfb8aa3b, v25
	v_fma_f32 v62, -v58, v59, 1.0
	v_fmac_f32_e32 v59, v62, v59
	v_div_scale_f32 v62, vcc, 1.0, v52, 1.0
	v_mul_f32_e32 v63, v62, v59
	v_fma_f32 v64, -v58, v63, v62
; __device__ __forceinline__ float sigmoidf_(float x) { return 1.f / (1.f + __expf(-x)); }
; __device__ __forceinline__ void phase_merge(const Params& P, u16* sA, u16* sB) {
;     ...
; #pragma unroll
;       for (int mi = 0; mi < 4; mi++)
; #pragma unroll
;         for (int ni = 0; ni < 4; ni++) {
;           f32x4 g = ag[mi][ni];
;           gp[mi][ni] = u32x2{pk2bf(sigmoidf_(g[0]), sigmoidf_(g[1])), pk2bf(sigmoidf_(g[2]), sigmoidf_(g[3]))};
;         }
	v_fmac_f32_e32 v63, v64, v59
	v_fma_f32 v58, -v58, v63, v62
	v_div_fmas_f32 v58, v58, v59, v63
	v_div_fixup_f32 v52, v58, v52, 1.0
	v_cvt_pk_bf16_f32 v52, v52, v53
	v_mul_f32_e32 v53, 0xbfb8aa3b, v54
	v_exp_f32_e32 v54, v53
	v_mul_f32_e32 v53, 0xbfb8aa3b, v55
	v_exp_f32_e32 v55, v53
	v_exp_f32_e32 v24, v24
	v_exp_f32_e32 v25, v25
	v_mul_f32_e32 v20, 0xbfb8aa3b, v20
	v_pk_add_f32 v[54:55], v[54:55], 1.0 op_sel_hi:[1,0]
	v_mul_f32_e32 v21, 0xbfb8aa3b, v21
	v_div_scale_f32 v53, s[22:23], v55, v55, 1.0
	v_rcp_f32_e32 v58, v53
	v_pk_add_f32 v[24:25], v[24:25], 1.0 op_sel_hi:[1,0]
	v_exp_f32_e32 v20, v20
	v_exp_f32_e32 v21, v21
	v_fma_f32 v59, -v53, v58, 1.0
	v_fmac_f32_e32 v58, v59, v58
	v_div_scale_f32 v59, vcc, 1.0, v55, 1.0
	v_mul_f32_e32 v62, v59, v58
	v_fma_f32 v63, -v53, v62, v59
	v_fmac_f32_e32 v62, v63, v58
	v_fma_f32 v53, -v53, v62, v59
	v_div_fmas_f32 v53, v53, v58, v62
	v_div_fixup_f32 v53, v53, v55, 1.0
	v_div_scale_f32 v55, s[22:23], v54, v54, 1.0
	v_rcp_f32_e32 v58, v55
	v_pk_add_f32 v[20:21], v[20:21], 1.0 op_sel_hi:[1,0]
	v_mul_f32_e32 v16, 0xbfb8aa3b, v16
	v_mul_f32_e32 v17, 0xbfb8aa3b, v17
	v_fma_f32 v59, -v55, v58, 1.0
	v_fmac_f32_e32 v58, v59, v58
	v_div_scale_f32 v59, vcc, 1.0, v54, 1.0
	v_mul_f32_e32 v62, v59, v58
	v_fma_f32 v63, -v55, v62, v59
	v_fmac_f32_e32 v62, v63, v58
	v_fma_f32 v55, -v55, v62, v59
	v_div_fmas_f32 v55, v55, v58, v62
	v_div_fixup_f32 v54, v55, v54, 1.0
	v_cvt_pk_bf16_f32 v53, v54, v53
	v_div_scale_f32 v54, s[22:23], v49, v49, 1.0
	v_rcp_f32_e32 v55, v54
	v_exp_f32_e32 v16, v16
	v_exp_f32_e32 v17, v17
	v_mul_f32_e32 v12, 0xbfb8aa3b, v12
	v_fma_f32 v58, -v54, v55, 1.0
	v_fmac_f32_e32 v55, v58, v55
	v_div_scale_f32 v58, vcc, 1.0, v49, 1.0
	v_mul_f32_e32 v59, v58, v55
	v_fma_f32 v62, -v54, v59, v58
	v_fmac_f32_e32 v59, v62, v55
	v_fma_f32 v54, -v54, v59, v58
	v_div_fmas_f32 v54, v54, v55, v59
	v_div_fixup_f32 v49, v54, v49, 1.0
	v_div_scale_f32 v54, s[22:23], v48, v48, 1.0
	v_rcp_f32_e32 v55, v54
	v_pk_add_f32 v[16:17], v[16:17], 1.0 op_sel_hi:[1,0]
	v_mul_f32_e32 v13, 0xbfb8aa3b, v13
	v_exp_f32_e32 v12, v12
	v_fma_f32 v58, -v54, v55, 1.0
	v_fmac_f32_e32 v55, v58, v55
	v_div_scale_f32 v58, vcc, 1.0, v48, 1.0
	v_mul_f32_e32 v59, v58, v55
	v_fma_f32 v62, -v54, v59, v58
	v_fmac_f32_e32 v59, v62, v55
	v_fma_f32 v54, -v54, v59, v58
	v_div_fmas_f32 v54, v54, v55, v59
	v_div_fixup_f32 v48, v54, v48, 1.0
	v_cvt_pk_bf16_f32 v54, v48, v49
	v_mul_f32_e32 v48, 0xbfb8aa3b, v50
	v_mul_f32_e32 v49, 0xbfb8aa3b, v51
	v_exp_f32_e32 v48, v48
	v_exp_f32_e32 v49, v49
	v_exp_f32_e32 v13, v13
	v_mul_f32_e32 v8, 0xbfb8aa3b, v8
	v_mul_f32_e32 v9, 0xbfb8aa3b, v9
	v_pk_add_f32 v[48:49], v[48:49], 1.0 op_sel_hi:[1,0]
	v_pk_add_f32 v[12:13], v[12:13], 1.0 op_sel_hi:[1,0]
	v_div_scale_f32 v50, s[22:23], v49, v49, 1.0
	v_rcp_f32_e32 v51, v50
	v_exp_f32_e32 v8, v8
	v_exp_f32_e32 v9, v9
	v_mul_f32_e32 v4, 0xbfb8aa3b, v4
	v_fma_f32 v55, -v50, v51, 1.0
	v_fmac_f32_e32 v51, v55, v51
	v_div_scale_f32 v55, vcc, 1.0, v49, 1.0
	v_mul_f32_e32 v58, v55, v51
	v_fma_f32 v59, -v50, v58, v55
	v_fmac_f32_e32 v58, v59, v51
	v_fma_f32 v50, -v50, v58, v55
	v_div_fmas_f32 v50, v50, v51, v58
	v_div_fixup_f32 v49, v50, v49, 1.0
	v_div_scale_f32 v50, s[22:23], v48, v48, 1.0
	v_rcp_f32_e32 v51, v50
	v_pk_add_f32 v[8:9], v[8:9], 1.0 op_sel_hi:[1,0]
	v_mul_f32_e32 v5, 0xbfb8aa3b, v5
	v_exp_f32_e32 v4, v4
	v_fma_f32 v55, -v50, v51, 1.0
	v_fmac_f32_e32 v51, v55, v51
	v_div_scale_f32 v55, vcc, 1.0, v48, 1.0
	v_mul_f32_e32 v58, v55, v51
	v_fma_f32 v59, -v50, v58, v55
	v_fmac_f32_e32 v58, v59, v51
	v_fma_f32 v50, -v50, v58, v55
	v_div_fmas_f32 v50, v50, v51, v58
	v_div_fixup_f32 v48, v50, v48, 1.0
	v_cvt_pk_bf16_f32 v50, v48, v49
	v_div_scale_f32 v48, s[22:23], v45, v45, 1.0
	v_rcp_f32_e32 v49, v48
	v_exp_f32_e32 v5, v5
	v_mul_f32_e32 v0, 0xbfb8aa3b, v0
	v_mul_f32_e32 v1, 0xbfb8aa3b, v1
	v_fma_f32 v51, -v48, v49, 1.0
	v_fmac_f32_e32 v49, v51, v49
	v_div_scale_f32 v51, vcc, 1.0, v45, 1.0
	v_mul_f32_e32 v55, v51, v49
	v_fma_f32 v58, -v48, v55, v51
	v_fmac_f32_e32 v55, v58, v49
	v_fma_f32 v48, -v48, v55, v51
	v_div_fmas_f32 v48, v48, v49, v55
	v_div_fixup_f32 v45, v48, v45, 1.0
	v_div_scale_f32 v48, s[22:23], v44, v44, 1.0
	v_rcp_f32_e32 v49, v48
	v_pk_add_f32 v[4:5], v[4:5], 1.0 op_sel_hi:[1,0]
	v_exp_f32_e32 v0, v0
	v_exp_f32_e32 v1, v1
	v_fma_f32 v51, -v48, v49, 1.0
	v_fmac_f32_e32 v49, v51, v49
	v_div_scale_f32 v51, vcc, 1.0, v44, 1.0
	v_mul_f32_e32 v55, v51, v49
	v_fma_f32 v58, -v48, v55, v51
	v_fmac_f32_e32 v55, v58, v49
	v_fma_f32 v48, -v48, v55, v51
	v_div_fmas_f32 v48, v48, v49, v55
	v_div_fixup_f32 v44, v48, v44, 1.0
	v_cvt_pk_bf16_f32 v51, v44, v45
	v_mul_f32_e32 v44, 0xbfb8aa3b, v46
	v_mul_f32_e32 v45, 0xbfb8aa3b, v47
	v_exp_f32_e32 v44, v44
	v_exp_f32_e32 v45, v45
	v_pk_add_f32 v[0:1], v[0:1], 1.0 op_sel_hi:[1,0]
	s_waitcnt vmcnt(2)
; __device__ __forceinline__ float sigmoidf_(float x) { return 1.f / (1.f + __expf(-x)); }
; __device__ __forceinline__ void phase_merge(const Params& P, u16* sA, u16* sB) {
;     ...
; #pragma unroll
;       for (int mi = 0; mi < 4; mi++)
; #pragma unroll
;         for (int ni = 0; ni < 4; ni++) {
;           f32x4 g = ag[mi][ni];
;           gp[mi][ni] = u32x2{pk2bf(sigmoidf_(g[0]), sigmoidf_(g[1])), pk2bf(sigmoidf_(g[2]), sigmoidf_(g[3]))};
;         }
	v_mov_b32_e32 v82, v169
	v_pk_add_f32 v[44:45], v[44:45], 1.0 op_sel_hi:[1,0]
	v_lshlrev_b32_e32 v83, 4, v82
	v_div_scale_f32 v46, s[22:23], v45, v45, 1.0
	v_rcp_f32_e32 v47, v46
	v_and_b32_e32 v130, 0x70, v83
	v_lshrrev_b32_e32 v84, 4, v82
	v_xor_b32_e32 v85, v84, v82
	v_fma_f32 v48, -v46, v47, 1.0
	v_fmac_f32_e32 v47, v48, v47
	v_div_scale_f32 v48, vcc, 1.0, v45, 1.0
	v_mul_f32_e32 v49, v48, v47
	v_fma_f32 v55, -v46, v49, v48
	v_fmac_f32_e32 v49, v55, v47
	v_fma_f32 v46, -v46, v49, v48
	v_div_fmas_f32 v46, v46, v47, v49
	v_div_fixup_f32 v45, v46, v45, 1.0
	v_div_scale_f32 v46, s[22:23], v44, v44, 1.0
	v_rcp_f32_e32 v47, v46
	v_lshlrev_b32_e32 v85, 4, v85
	v_and_b32_e32 v85, 0x70, v85
	v_and_b32_e32 v86, 15, v82
	v_fma_f32 v48, -v46, v47, 1.0
	v_fmac_f32_e32 v47, v48, v47
	v_div_scale_f32 v48, vcc, 1.0, v44, 1.0
	v_mul_f32_e32 v49, v48, v47
	v_fma_f32 v55, -v46, v49, v48
	v_fmac_f32_e32 v49, v55, v47
	v_fma_f32 v46, -v46, v49, v48
	v_div_fmas_f32 v46, v46, v47, v49
	v_div_fixup_f32 v44, v46, v44, 1.0
	v_cvt_pk_bf16_f32 v55, v44, v45
	v_div_scale_f32 v44, s[22:23], v41, v41, 1.0
	v_rcp_f32_e32 v45, v44
	v_bfe_u32 v87, v82, 1, 3
	v_lshlrev_b32_e32 v86, 7, v86
	s_movk_i32 s21, 0x800
	v_fma_f32 v46, -v44, v45, 1.0
	v_fmac_f32_e32 v45, v46, v45
	v_div_scale_f32 v46, vcc, 1.0, v41, 1.0
	v_mul_f32_e32 v47, v46, v45
	v_fma_f32 v48, -v44, v47, v46
	v_fmac_f32_e32 v47, v48, v45
	v_fma_f32 v44, -v44, v47, v46
	v_div_fmas_f32 v44, v44, v45, v47
	v_div_fixup_f32 v41, v44, v41, 1.0
	v_div_scale_f32 v44, s[22:23], v40, v40, 1.0
	v_rcp_f32_e32 v45, v44
	v_bitop3_b32 v84, v84, v87, 3 bitop3:0x6c
	v_lshlrev_b32_e32 v84, 4, v84
	v_fma_f32 v46, -v44, v45, 1.0
	v_fmac_f32_e32 v45, v46, v45
	v_div_scale_f32 v46, vcc, 1.0, v40, 1.0
	v_mul_f32_e32 v47, v46, v45
	v_fma_f32 v48, -v44, v47, v46
	v_fmac_f32_e32 v47, v48, v45
	v_fma_f32 v44, -v44, v47, v46
	v_div_fmas_f32 v44, v44, v45, v47
	v_div_fixup_f32 v40, v44, v40, 1.0
	v_cvt_pk_bf16_f32 v58, v40, v41
	v_mul_f32_e32 v40, 0xbfb8aa3b, v42
	v_mul_f32_e32 v41, 0xbfb8aa3b, v43
	v_exp_f32_e32 v40, v40
	v_exp_f32_e32 v41, v41
	s_nop 0
	v_pk_add_f32 v[40:41], v[40:41], 1.0 op_sel_hi:[1,0]
	s_nop 0
	v_div_scale_f32 v42, s[22:23], v41, v41, 1.0
	v_rcp_f32_e32 v43, v42
	s_nop 0
	v_fma_f32 v44, -v42, v43, 1.0
	v_fmac_f32_e32 v43, v44, v43
	v_div_scale_f32 v44, vcc, 1.0, v41, 1.0
	v_mul_f32_e32 v45, v44, v43
	v_fma_f32 v46, -v42, v45, v44
	v_fmac_f32_e32 v45, v46, v43
	v_fma_f32 v42, -v42, v45, v44
	v_div_fmas_f32 v42, v42, v43, v45
	v_div_fixup_f32 v41, v42, v41, 1.0
	v_div_scale_f32 v42, s[22:23], v40, v40, 1.0
	v_rcp_f32_e32 v43, v42
	s_nop 0
	v_fma_f32 v44, -v42, v43, 1.0
	v_fmac_f32_e32 v43, v44, v43
	v_div_scale_f32 v44, vcc, 1.0, v40, 1.0
	v_mul_f32_e32 v45, v44, v43
	v_fma_f32 v46, -v42, v45, v44
	v_fmac_f32_e32 v45, v46, v43
	v_fma_f32 v42, -v42, v45, v44
	v_div_fmas_f32 v42, v42, v43, v45
	v_div_fixup_f32 v40, v42, v40, 1.0
	v_cvt_pk_bf16_f32 v59, v40, v41
	v_div_scale_f32 v40, s[22:23], v37, v37, 1.0
	v_rcp_f32_e32 v41, v40
	s_nop 0
	v_fma_f32 v42, -v40, v41, 1.0
	v_fmac_f32_e32 v41, v42, v41
	v_div_scale_f32 v42, vcc, 1.0, v37, 1.0
	v_mul_f32_e32 v43, v42, v41
	v_fma_f32 v44, -v40, v43, v42
	v_fmac_f32_e32 v43, v44, v41
	v_fma_f32 v40, -v40, v43, v42
	v_div_fmas_f32 v40, v40, v41, v43
	v_div_fixup_f32 v37, v40, v37, 1.0
	v_div_scale_f32 v40, s[22:23], v36, v36, 1.0
	v_rcp_f32_e32 v41, v40
	s_nop 0
	v_fma_f32 v42, -v40, v41, 1.0
	v_fmac_f32_e32 v41, v42, v41
	v_div_scale_f32 v42, vcc, 1.0, v36, 1.0
	v_mul_f32_e32 v43, v42, v41
	v_fma_f32 v44, -v40, v43, v42
	v_fmac_f32_e32 v43, v44, v41
	v_fma_f32 v40, -v40, v43, v42
	v_div_fmas_f32 v40, v40, v41, v43
	v_div_fixup_f32 v36, v40, v36, 1.0
	v_cvt_pk_bf16_f32 v62, v36, v37
	v_mul_f32_e32 v36, 0xbfb8aa3b, v38
	v_mul_f32_e32 v37, 0xbfb8aa3b, v39
	v_exp_f32_e32 v36, v36
	v_exp_f32_e32 v37, v37
	s_nop 0
	v_pk_add_f32 v[36:37], v[36:37], 1.0 op_sel_hi:[1,0]
	s_nop 0
	v_div_scale_f32 v38, s[22:23], v37, v37, 1.0
	v_rcp_f32_e32 v39, v38
	s_nop 0
	v_fma_f32 v40, -v38, v39, 1.0
	v_fmac_f32_e32 v39, v40, v39
	v_div_scale_f32 v40, vcc, 1.0, v37, 1.0
	v_mul_f32_e32 v41, v40, v39
	v_fma_f32 v42, -v38, v41, v40
	v_fmac_f32_e32 v41, v42, v39
	v_fma_f32 v38, -v38, v41, v40
	v_div_fmas_f32 v38, v38, v39, v41
	v_div_fixup_f32 v37, v38, v37, 1.0
	v_div_scale_f32 v38, s[22:23], v36, v36, 1.0
	v_rcp_f32_e32 v39, v38
	s_nop 0
	v_fma_f32 v40, -v38, v39, 1.0
	v_fmac_f32_e32 v39, v40, v39
	v_div_scale_f32 v40, vcc, 1.0, v36, 1.0
	v_mul_f32_e32 v41, v40, v39
	v_fma_f32 v42, -v38, v41, v40
	v_fmac_f32_e32 v41, v42, v39
	v_fma_f32 v38, -v38, v41, v40
	v_div_fmas_f32 v38, v38, v39, v41
	v_div_fixup_f32 v36, v38, v36, 1.0
	v_cvt_pk_bf16_f32 v63, v36, v37
	v_div_scale_f32 v36, s[22:23], v33, v33, 1.0
	v_rcp_f32_e32 v37, v36
	s_nop 0
	v_fma_f32 v38, -v36, v37, 1.0
	v_fmac_f32_e32 v37, v38, v37
	v_div_scale_f32 v38, vcc, 1.0, v33, 1.0
	v_mul_f32_e32 v39, v38, v37
	v_fma_f32 v40, -v36, v39, v38
	v_fmac_f32_e32 v39, v40, v37
	v_fma_f32 v36, -v36, v39, v38
	v_div_fmas_f32 v36, v36, v37, v39
	v_div_fixup_f32 v33, v36, v33, 1.0
	v_div_scale_f32 v36, s[22:23], v32, v32, 1.0
	v_rcp_f32_e32 v37, v36
	s_nop 0
	v_fma_f32 v38, -v36, v37, 1.0
	v_fmac_f32_e32 v37, v38, v37
	v_div_scale_f32 v38, vcc, 1.0, v32, 1.0
	v_mul_f32_e32 v39, v38, v37
	v_fma_f32 v40, -v36, v39, v38
	v_fmac_f32_e32 v39, v40, v37
	v_fma_f32 v36, -v36, v39, v38
	v_div_fmas_f32 v36, v36, v37, v39
	v_div_fixup_f32 v32, v36, v32, 1.0
	v_cvt_pk_bf16_f32 v64, v32, v33
	v_mul_f32_e32 v32, 0xbfb8aa3b, v34
	v_mul_f32_e32 v33, 0xbfb8aa3b, v35
	v_exp_f32_e32 v32, v32
	v_exp_f32_e32 v33, v33
	s_nop 0
	v_pk_add_f32 v[32:33], v[32:33], 1.0 op_sel_hi:[1,0]
; __device__ __forceinline__ float sigmoidf_(float x) { return 1.f / (1.f + __expf(-x)); }
; __device__ __forceinline__ void phase_merge(const Params& P, u16* sA, u16* sB) {
;     ...
; #pragma unroll
;       for (int mi = 0; mi < 4; mi++)
; #pragma unroll
;         for (int ni = 0; ni < 4; ni++) {
;           f32x4 g = ag[mi][ni];
;           gp[mi][ni] = u32x2{pk2bf(sigmoidf_(g[0]), sigmoidf_(g[1])), pk2bf(sigmoidf_(g[2]), sigmoidf_(g[3]))};
;         }
	s_nop 0
	v_div_scale_f32 v34, s[22:23], v33, v33, 1.0
	v_rcp_f32_e32 v35, v34
	s_nop 0
	v_fma_f32 v36, -v34, v35, 1.0
	v_fmac_f32_e32 v35, v36, v35
	v_div_scale_f32 v36, vcc, 1.0, v33, 1.0
	v_mul_f32_e32 v37, v36, v35
	v_fma_f32 v38, -v34, v37, v36
	v_fmac_f32_e32 v37, v38, v35
	v_fma_f32 v34, -v34, v37, v36
	v_div_fmas_f32 v34, v34, v35, v37
	v_div_fixup_f32 v33, v34, v33, 1.0
	v_div_scale_f32 v34, s[22:23], v32, v32, 1.0
	v_rcp_f32_e32 v35, v34
	s_nop 0
	v_fma_f32 v36, -v34, v35, 1.0
	v_fmac_f32_e32 v35, v36, v35
	v_div_scale_f32 v36, vcc, 1.0, v32, 1.0
	v_mul_f32_e32 v37, v36, v35
	v_fma_f32 v38, -v34, v37, v36
	v_fmac_f32_e32 v37, v38, v35
	v_fma_f32 v34, -v34, v37, v36
	v_div_fmas_f32 v34, v34, v35, v37
	v_div_fixup_f32 v32, v34, v32, 1.0
	v_cvt_pk_bf16_f32 v65, v32, v33
	v_div_scale_f32 v32, s[22:23], v29, v29, 1.0
	v_rcp_f32_e32 v33, v32
	s_nop 0
	v_fma_f32 v34, -v32, v33, 1.0
	v_fmac_f32_e32 v33, v34, v33
	v_div_scale_f32 v34, vcc, 1.0, v29, 1.0
	v_mul_f32_e32 v35, v34, v33
	v_fma_f32 v36, -v32, v35, v34
	v_fmac_f32_e32 v35, v36, v33
	v_fma_f32 v32, -v32, v35, v34
	v_div_fmas_f32 v32, v32, v33, v35
	v_div_fixup_f32 v29, v32, v29, 1.0
	v_div_scale_f32 v32, s[22:23], v28, v28, 1.0
	v_rcp_f32_e32 v33, v32
	s_nop 0
	v_fma_f32 v34, -v32, v33, 1.0
	v_fmac_f32_e32 v33, v34, v33
	v_div_scale_f32 v34, vcc, 1.0, v28, 1.0
	v_mul_f32_e32 v35, v34, v33
	v_fma_f32 v36, -v32, v35, v34
	v_fmac_f32_e32 v35, v36, v33
	v_fma_f32 v32, -v32, v35, v34
	v_div_fmas_f32 v32, v32, v33, v35
	v_div_fixup_f32 v28, v32, v28, 1.0
	v_cvt_pk_bf16_f32 v66, v28, v29
	v_mul_f32_e32 v28, 0xbfb8aa3b, v30
	v_mul_f32_e32 v29, 0xbfb8aa3b, v31
	v_exp_f32_e32 v28, v28
	v_exp_f32_e32 v29, v29
	s_nop 0
	v_pk_add_f32 v[28:29], v[28:29], 1.0 op_sel_hi:[1,0]
	s_nop 0
	v_div_scale_f32 v30, s[22:23], v29, v29, 1.0
	v_rcp_f32_e32 v31, v30
	s_nop 0
	v_fma_f32 v32, -v30, v31, 1.0
	v_fmac_f32_e32 v31, v32, v31
	v_div_scale_f32 v32, vcc, 1.0, v29, 1.0
	v_mul_f32_e32 v33, v32, v31
	v_fma_f32 v34, -v30, v33, v32
	v_fmac_f32_e32 v33, v34, v31
	v_fma_f32 v30, -v30, v33, v32
	v_div_fmas_f32 v30, v30, v31, v33
	v_div_fixup_f32 v29, v30, v29, 1.0
	v_div_scale_f32 v30, s[22:23], v28, v28, 1.0
	v_rcp_f32_e32 v31, v30
	s_nop 0
	v_fma_f32 v32, -v30, v31, 1.0
	v_fmac_f32_e32 v31, v32, v31
	v_div_scale_f32 v32, vcc, 1.0, v28, 1.0
	v_mul_f32_e32 v33, v32, v31
	v_fma_f32 v34, -v30, v33, v32
	v_fmac_f32_e32 v33, v34, v31
	v_fma_f32 v30, -v30, v33, v32
	v_div_fmas_f32 v30, v30, v31, v33
	v_div_fixup_f32 v28, v30, v28, 1.0
	v_cvt_pk_bf16_f32 v67, v28, v29
	v_div_scale_f32 v28, s[22:23], v25, v25, 1.0
	v_rcp_f32_e32 v29, v28
	s_nop 0
	v_fma_f32 v30, -v28, v29, 1.0
	v_fmac_f32_e32 v29, v30, v29
	v_div_scale_f32 v30, vcc, 1.0, v25, 1.0
	v_mul_f32_e32 v31, v30, v29
	v_fma_f32 v32, -v28, v31, v30
	v_fmac_f32_e32 v31, v32, v29
	v_fma_f32 v28, -v28, v31, v30
	v_div_fmas_f32 v28, v28, v29, v31
	v_div_fixup_f32 v25, v28, v25, 1.0
	v_div_scale_f32 v28, s[22:23], v24, v24, 1.0
	v_rcp_f32_e32 v29, v28
	s_nop 0
	v_fma_f32 v30, -v28, v29, 1.0
	v_fmac_f32_e32 v29, v30, v29
	v_div_scale_f32 v30, vcc, 1.0, v24, 1.0
	v_mul_f32_e32 v31, v30, v29
	v_fma_f32 v32, -v28, v31, v30
	v_fmac_f32_e32 v31, v32, v29
	v_fma_f32 v28, -v28, v31, v30
	v_div_fmas_f32 v28, v28, v29, v31
	v_div_fixup_f32 v24, v28, v24, 1.0
	v_cvt_pk_bf16_f32 v68, v24, v25
	v_mul_f32_e32 v24, 0xbfb8aa3b, v26
	v_mul_f32_e32 v25, 0xbfb8aa3b, v27
	v_exp_f32_e32 v24, v24
	v_exp_f32_e32 v25, v25
	s_nop 0
	v_pk_add_f32 v[24:25], v[24:25], 1.0 op_sel_hi:[1,0]
	s_nop 0
	v_div_scale_f32 v26, s[22:23], v25, v25, 1.0
	v_rcp_f32_e32 v27, v26
	s_nop 0
	v_fma_f32 v28, -v26, v27, 1.0
	v_fmac_f32_e32 v27, v28, v27
	v_div_scale_f32 v28, vcc, 1.0, v25, 1.0
	v_mul_f32_e32 v29, v28, v27
	v_fma_f32 v30, -v26, v29, v28
	v_fmac_f32_e32 v29, v30, v27
	v_fma_f32 v26, -v26, v29, v28
	v_div_fmas_f32 v26, v26, v27, v29
	v_div_fixup_f32 v25, v26, v25, 1.0
	v_div_scale_f32 v26, s[22:23], v24, v24, 1.0
	v_rcp_f32_e32 v27, v26
	s_nop 0
	v_fma_f32 v28, -v26, v27, 1.0
	v_fmac_f32_e32 v27, v28, v27
	v_div_scale_f32 v28, vcc, 1.0, v24, 1.0
	v_mul_f32_e32 v29, v28, v27
	v_fma_f32 v30, -v26, v29, v28
	v_fmac_f32_e32 v29, v30, v27
	v_fma_f32 v26, -v26, v29, v28
	v_div_fmas_f32 v26, v26, v27, v29
	v_div_fixup_f32 v24, v26, v24, 1.0
	v_cvt_pk_bf16_f32 v69, v24, v25
	v_div_scale_f32 v24, s[22:23], v21, v21, 1.0
	v_rcp_f32_e32 v25, v24
	s_nop 0
	v_fma_f32 v26, -v24, v25, 1.0
	v_fmac_f32_e32 v25, v26, v25
	v_div_scale_f32 v26, vcc, 1.0, v21, 1.0
	v_mul_f32_e32 v27, v26, v25
	v_fma_f32 v28, -v24, v27, v26
	v_fmac_f32_e32 v27, v28, v25
	v_fma_f32 v24, -v24, v27, v26
	v_div_fmas_f32 v24, v24, v25, v27
	v_div_fixup_f32 v21, v24, v21, 1.0
	v_div_scale_f32 v24, s[22:23], v20, v20, 1.0
	v_rcp_f32_e32 v25, v24
	s_nop 0
	v_fma_f32 v26, -v24, v25, 1.0
	v_fmac_f32_e32 v25, v26, v25
	v_div_scale_f32 v26, vcc, 1.0, v20, 1.0
	v_mul_f32_e32 v27, v26, v25
	v_fma_f32 v28, -v24, v27, v26
	v_fmac_f32_e32 v27, v28, v25
	v_fma_f32 v24, -v24, v27, v26
	v_div_fmas_f32 v24, v24, v25, v27
	v_div_fixup_f32 v20, v24, v20, 1.0
	v_cvt_pk_bf16_f32 v70, v20, v21
	v_mul_f32_e32 v20, 0xbfb8aa3b, v22
	v_mul_f32_e32 v21, 0xbfb8aa3b, v23
	v_exp_f32_e32 v20, v20
	v_exp_f32_e32 v21, v21
	s_nop 0
	v_pk_add_f32 v[20:21], v[20:21], 1.0 op_sel_hi:[1,0]
	s_nop 0
	v_div_scale_f32 v22, s[22:23], v21, v21, 1.0
	v_rcp_f32_e32 v23, v22
	s_nop 0
	v_fma_f32 v24, -v22, v23, 1.0
	v_fmac_f32_e32 v23, v24, v23
	v_div_scale_f32 v24, vcc, 1.0, v21, 1.0
	v_mul_f32_e32 v25, v24, v23
	v_fma_f32 v26, -v22, v25, v24
	v_fmac_f32_e32 v25, v26, v23
	v_fma_f32 v22, -v22, v25, v24
	v_div_fmas_f32 v22, v22, v23, v25
	v_div_fixup_f32 v21, v22, v21, 1.0
; __device__ __forceinline__ float sigmoidf_(float x) { return 1.f / (1.f + __expf(-x)); }
; __device__ __forceinline__ void phase_merge(const Params& P, u16* sA, u16* sB) {
;     ...
; #pragma unroll
;       for (int mi = 0; mi < 4; mi++)
; #pragma unroll
;         for (int ni = 0; ni < 4; ni++) {
;           f32x4 g = ag[mi][ni];
;           gp[mi][ni] = u32x2{pk2bf(sigmoidf_(g[0]), sigmoidf_(g[1])), pk2bf(sigmoidf_(g[2]), sigmoidf_(g[3]))};
;         }
	v_div_scale_f32 v22, s[22:23], v20, v20, 1.0
	v_rcp_f32_e32 v23, v22
	s_nop 0
	v_fma_f32 v24, -v22, v23, 1.0
	v_fmac_f32_e32 v23, v24, v23
	v_div_scale_f32 v24, vcc, 1.0, v20, 1.0
	v_mul_f32_e32 v25, v24, v23
	v_fma_f32 v26, -v22, v25, v24
	v_fmac_f32_e32 v25, v26, v23
	v_fma_f32 v22, -v22, v25, v24
	v_div_fmas_f32 v22, v22, v23, v25
	v_div_fixup_f32 v20, v22, v20, 1.0
	v_cvt_pk_bf16_f32 v71, v20, v21
	v_div_scale_f32 v20, s[22:23], v17, v17, 1.0
	v_rcp_f32_e32 v21, v20
	s_nop 0
	v_fma_f32 v22, -v20, v21, 1.0
	v_fmac_f32_e32 v21, v22, v21
	v_div_scale_f32 v22, vcc, 1.0, v17, 1.0
	v_mul_f32_e32 v23, v22, v21
	v_fma_f32 v24, -v20, v23, v22
	v_fmac_f32_e32 v23, v24, v21
	v_fma_f32 v20, -v20, v23, v22
	v_div_fmas_f32 v20, v20, v21, v23
	v_div_fixup_f32 v17, v20, v17, 1.0
	v_div_scale_f32 v20, s[22:23], v16, v16, 1.0
	v_rcp_f32_e32 v21, v20
	s_nop 0
	v_fma_f32 v22, -v20, v21, 1.0
	v_fmac_f32_e32 v21, v22, v21
	v_div_scale_f32 v22, vcc, 1.0, v16, 1.0
	v_mul_f32_e32 v23, v22, v21
	v_fma_f32 v24, -v20, v23, v22
	v_fmac_f32_e32 v23, v24, v21
	v_fma_f32 v20, -v20, v23, v22
	v_div_fmas_f32 v20, v20, v21, v23
	v_div_fixup_f32 v16, v20, v16, 1.0
	v_cvt_pk_bf16_f32 v72, v16, v17
	v_mul_f32_e32 v16, 0xbfb8aa3b, v18
	v_mul_f32_e32 v17, 0xbfb8aa3b, v19
	v_exp_f32_e32 v16, v16
	v_exp_f32_e32 v17, v17
	s_nop 0
	v_pk_add_f32 v[16:17], v[16:17], 1.0 op_sel_hi:[1,0]
	s_nop 0
	v_div_scale_f32 v18, s[22:23], v17, v17, 1.0
	v_rcp_f32_e32 v19, v18
	s_nop 0
	v_fma_f32 v20, -v18, v19, 1.0
	v_fmac_f32_e32 v19, v20, v19
	v_div_scale_f32 v20, vcc, 1.0, v17, 1.0
	v_mul_f32_e32 v21, v20, v19
	v_fma_f32 v22, -v18, v21, v20
	v_fmac_f32_e32 v21, v22, v19
	v_fma_f32 v18, -v18, v21, v20
	v_div_fmas_f32 v18, v18, v19, v21
	v_div_fixup_f32 v17, v18, v17, 1.0
	v_div_scale_f32 v18, s[22:23], v16, v16, 1.0
	v_rcp_f32_e32 v19, v18
	s_nop 0
	v_fma_f32 v20, -v18, v19, 1.0
	v_fmac_f32_e32 v19, v20, v19
	v_div_scale_f32 v20, vcc, 1.0, v16, 1.0
	v_mul_f32_e32 v21, v20, v19
	v_fma_f32 v22, -v18, v21, v20
	v_fmac_f32_e32 v21, v22, v19
	v_fma_f32 v18, -v18, v21, v20
	v_div_fmas_f32 v18, v18, v19, v21
	v_div_fixup_f32 v16, v18, v16, 1.0
	v_cvt_pk_bf16_f32 v73, v16, v17
	v_div_scale_f32 v16, s[22:23], v13, v13, 1.0
	v_rcp_f32_e32 v17, v16
	s_nop 0
	v_fma_f32 v18, -v16, v17, 1.0
	v_fmac_f32_e32 v17, v18, v17
	v_div_scale_f32 v18, vcc, 1.0, v13, 1.0
	v_mul_f32_e32 v19, v18, v17
	v_fma_f32 v20, -v16, v19, v18
	v_fmac_f32_e32 v19, v20, v17
	v_fma_f32 v16, -v16, v19, v18
	v_div_fmas_f32 v16, v16, v17, v19
	v_div_fixup_f32 v13, v16, v13, 1.0
	v_div_scale_f32 v16, s[22:23], v12, v12, 1.0
	v_rcp_f32_e32 v17, v16
	s_nop 0
	v_fma_f32 v18, -v16, v17, 1.0
	v_fmac_f32_e32 v17, v18, v17
	v_div_scale_f32 v18, vcc, 1.0, v12, 1.0
	v_mul_f32_e32 v19, v18, v17
	v_fma_f32 v20, -v16, v19, v18
	v_fmac_f32_e32 v19, v20, v17
	v_fma_f32 v16, -v16, v19, v18
	v_div_fmas_f32 v16, v16, v17, v19
	v_div_fixup_f32 v12, v16, v12, 1.0
	v_cvt_pk_bf16_f32 v74, v12, v13
	v_mul_f32_e32 v12, 0xbfb8aa3b, v14
	v_mul_f32_e32 v13, 0xbfb8aa3b, v15
	v_exp_f32_e32 v12, v12
	v_exp_f32_e32 v13, v13
	s_nop 0
	v_pk_add_f32 v[12:13], v[12:13], 1.0 op_sel_hi:[1,0]
	s_nop 0
	v_div_scale_f32 v14, s[22:23], v13, v13, 1.0
	v_rcp_f32_e32 v15, v14
	s_nop 0
	v_fma_f32 v16, -v14, v15, 1.0
	v_fmac_f32_e32 v15, v16, v15
	v_div_scale_f32 v16, vcc, 1.0, v13, 1.0
	v_mul_f32_e32 v17, v16, v15
	v_fma_f32 v18, -v14, v17, v16
	v_fmac_f32_e32 v17, v18, v15
	v_fma_f32 v14, -v14, v17, v16
	v_div_fmas_f32 v14, v14, v15, v17
	v_div_fixup_f32 v13, v14, v13, 1.0
	v_div_scale_f32 v14, s[22:23], v12, v12, 1.0
	v_rcp_f32_e32 v15, v14
	s_nop 0
	v_fma_f32 v16, -v14, v15, 1.0
	v_fmac_f32_e32 v15, v16, v15
	v_div_scale_f32 v16, vcc, 1.0, v12, 1.0
	v_mul_f32_e32 v17, v16, v15
	v_fma_f32 v18, -v14, v17, v16
	v_fmac_f32_e32 v17, v18, v15
	v_fma_f32 v14, -v14, v17, v16
	v_div_fmas_f32 v14, v14, v15, v17
	v_div_fixup_f32 v12, v14, v12, 1.0
	v_cvt_pk_bf16_f32 v75, v12, v13
	v_div_scale_f32 v12, s[22:23], v9, v9, 1.0
	v_rcp_f32_e32 v13, v12
	s_nop 0
	v_fma_f32 v14, -v12, v13, 1.0
	v_fmac_f32_e32 v13, v14, v13
	v_div_scale_f32 v14, vcc, 1.0, v9, 1.0
	v_mul_f32_e32 v15, v14, v13
	v_fma_f32 v16, -v12, v15, v14
	v_fmac_f32_e32 v15, v16, v13
	v_fma_f32 v12, -v12, v15, v14
	v_div_fmas_f32 v12, v12, v13, v15
	v_div_fixup_f32 v9, v12, v9, 1.0
	v_div_scale_f32 v12, s[22:23], v8, v8, 1.0
	v_rcp_f32_e32 v13, v12
	s_nop 0
	v_fma_f32 v14, -v12, v13, 1.0
	v_fmac_f32_e32 v13, v14, v13
	v_div_scale_f32 v14, vcc, 1.0, v8, 1.0
	v_mul_f32_e32 v15, v14, v13
	v_fma_f32 v16, -v12, v15, v14
	v_fmac_f32_e32 v15, v16, v13
	v_fma_f32 v12, -v12, v15, v14
	v_div_fmas_f32 v12, v12, v13, v15
	v_div_fixup_f32 v8, v12, v8, 1.0
	v_cvt_pk_bf16_f32 v76, v8, v9
	v_mul_f32_e32 v8, 0xbfb8aa3b, v10
	v_mul_f32_e32 v9, 0xbfb8aa3b, v11
	v_exp_f32_e32 v8, v8
	v_exp_f32_e32 v9, v9
	s_nop 0
	v_pk_add_f32 v[8:9], v[8:9], 1.0 op_sel_hi:[1,0]
	s_nop 0
	v_div_scale_f32 v10, s[22:23], v9, v9, 1.0
	v_rcp_f32_e32 v11, v10
	s_nop 0
	v_fma_f32 v12, -v10, v11, 1.0
	v_fmac_f32_e32 v11, v12, v11
	v_div_scale_f32 v12, vcc, 1.0, v9, 1.0
	v_mul_f32_e32 v13, v12, v11
	v_fma_f32 v14, -v10, v13, v12
	v_fmac_f32_e32 v13, v14, v11
	v_fma_f32 v10, -v10, v13, v12
	v_div_fmas_f32 v10, v10, v11, v13
	v_div_fixup_f32 v9, v10, v9, 1.0
	v_div_scale_f32 v10, s[22:23], v8, v8, 1.0
	v_rcp_f32_e32 v11, v10
	s_nop 0
	v_fma_f32 v12, -v10, v11, 1.0
	v_fmac_f32_e32 v11, v12, v11
	v_div_scale_f32 v12, vcc, 1.0, v8, 1.0
	v_mul_f32_e32 v13, v12, v11
	v_fma_f32 v14, -v10, v13, v12
	v_fmac_f32_e32 v13, v14, v11
	v_fma_f32 v10, -v10, v13, v12
	v_div_fmas_f32 v10, v10, v11, v13
	v_div_fixup_f32 v8, v10, v8, 1.0
	v_cvt_pk_bf16_f32 v77, v8, v9
; __device__ __forceinline__ float sigmoidf_(float x) { return 1.f / (1.f + __expf(-x)); }
; __device__ __forceinline__ void phase_merge(const Params& P, u16* sA, u16* sB) {
;     ...
; #pragma unroll
;       for (int mi = 0; mi < 4; mi++)
; #pragma unroll
;         for (int ni = 0; ni < 4; ni++) {
;           f32x4 g = ag[mi][ni];
;           gp[mi][ni] = u32x2{pk2bf(sigmoidf_(g[0]), sigmoidf_(g[1])), pk2bf(sigmoidf_(g[2]), sigmoidf_(g[3]))};
;         }
;     }
;     f32x4 macc[4];
; #pragma unroll
;     for (int mi = 0; mi < 4; mi++) macc[mi] = f32x4{0.f, 0.f, 0.f, 0.f};
; #pragma unroll
;     for (int i = 0; i < 4; i++) {
;       f32x4 ap[4][1];
;       zero_acc<1>(ap);
;       gemm_main<1>(Y + i * 256, 1024, (const u16*)(ws + O_WB) + (size_t)i * 1024 * 256, 256, 256, m0, n0, ap, sA, sB);
	v_div_scale_f32 v8, s[22:23], v5, v5, 1.0
	v_rcp_f32_e32 v9, v8
	s_nop 0
	v_fma_f32 v10, -v8, v9, 1.0
	v_fmac_f32_e32 v9, v10, v9
	v_div_scale_f32 v10, vcc, 1.0, v5, 1.0
	v_mul_f32_e32 v11, v10, v9
	v_fma_f32 v12, -v8, v11, v10
	v_fmac_f32_e32 v11, v12, v9
	v_fma_f32 v8, -v8, v11, v10
	v_div_fmas_f32 v8, v8, v9, v11
	v_div_fixup_f32 v5, v8, v5, 1.0
	v_div_scale_f32 v8, s[22:23], v4, v4, 1.0
	v_rcp_f32_e32 v9, v8
	s_nop 0
	v_fma_f32 v10, -v8, v9, 1.0
	v_fmac_f32_e32 v9, v10, v9
	v_div_scale_f32 v10, vcc, 1.0, v4, 1.0
	v_mul_f32_e32 v11, v10, v9
	v_fma_f32 v12, -v8, v11, v10
	v_fmac_f32_e32 v11, v12, v9
	v_fma_f32 v8, -v8, v11, v10
	v_div_fmas_f32 v8, v8, v9, v11
	v_div_fixup_f32 v4, v8, v4, 1.0
	v_cvt_pk_bf16_f32 v78, v4, v5
	v_mul_f32_e32 v4, 0xbfb8aa3b, v6
	v_mul_f32_e32 v5, 0xbfb8aa3b, v7
	v_exp_f32_e32 v4, v4
	v_exp_f32_e32 v5, v5
	s_nop 0
	v_pk_add_f32 v[4:5], v[4:5], 1.0 op_sel_hi:[1,0]
	s_nop 0
	v_div_scale_f32 v6, s[22:23], v5, v5, 1.0
	v_rcp_f32_e32 v7, v6
	s_nop 0
	v_fma_f32 v8, -v6, v7, 1.0
	v_fmac_f32_e32 v7, v8, v7
	v_div_scale_f32 v8, vcc, 1.0, v5, 1.0
	v_mul_f32_e32 v9, v8, v7
	v_fma_f32 v10, -v6, v9, v8
	v_fmac_f32_e32 v9, v10, v7
	v_fma_f32 v6, -v6, v9, v8
	v_div_fmas_f32 v6, v6, v7, v9
	v_div_fixup_f32 v5, v6, v5, 1.0
	v_div_scale_f32 v6, s[22:23], v4, v4, 1.0
	v_rcp_f32_e32 v7, v6
	s_nop 0
	v_fma_f32 v8, -v6, v7, 1.0
	v_fmac_f32_e32 v7, v8, v7
	v_div_scale_f32 v8, vcc, 1.0, v4, 1.0
	v_mul_f32_e32 v9, v8, v7
	v_fma_f32 v10, -v6, v9, v8
	v_fmac_f32_e32 v9, v10, v7
	v_fma_f32 v6, -v6, v9, v8
	v_div_fmas_f32 v6, v6, v7, v9
	v_div_fixup_f32 v4, v6, v4, 1.0
	v_cvt_pk_bf16_f32 v79, v4, v5
	v_div_scale_f32 v4, s[22:23], v1, v1, 1.0
	v_rcp_f32_e32 v5, v4
	s_nop 0
	v_fma_f32 v6, -v4, v5, 1.0
	v_fmac_f32_e32 v5, v6, v5
	v_div_scale_f32 v6, vcc, 1.0, v1, 1.0
	v_mul_f32_e32 v7, v6, v5
	v_fma_f32 v8, -v4, v7, v6
	v_fmac_f32_e32 v7, v8, v5
	v_fma_f32 v4, -v4, v7, v6
	v_div_fmas_f32 v4, v4, v5, v7
	v_div_fixup_f32 v1, v4, v1, 1.0
	v_div_scale_f32 v4, s[22:23], v0, v0, 1.0
	v_rcp_f32_e32 v5, v4
	s_nop 0
	v_fma_f32 v6, -v4, v5, 1.0
	v_fmac_f32_e32 v5, v6, v5
	v_div_scale_f32 v6, vcc, 1.0, v0, 1.0
	v_mul_f32_e32 v7, v6, v5
	v_fma_f32 v8, -v4, v7, v6
	v_fmac_f32_e32 v7, v8, v5
	v_fma_f32 v4, -v4, v7, v6
	v_div_fmas_f32 v4, v4, v5, v7
	v_div_fixup_f32 v0, v4, v0, 1.0
	v_cvt_pk_bf16_f32 v80, v0, v1
	v_mul_f32_e32 v0, 0xbfb8aa3b, v2
	v_mul_f32_e32 v1, 0xbfb8aa3b, v3
	v_exp_f32_e32 v0, v0
	v_exp_f32_e32 v1, v1
	s_nop 0
	v_pk_add_f32 v[0:1], v[0:1], 1.0 op_sel_hi:[1,0]
	s_nop 0
	v_div_scale_f32 v2, s[22:23], v1, v1, 1.0
	v_rcp_f32_e32 v3, v2
	s_nop 0
	v_fma_f32 v4, -v2, v3, 1.0
	v_fmac_f32_e32 v3, v4, v3
	v_div_scale_f32 v4, vcc, 1.0, v1, 1.0
	v_mul_f32_e32 v5, v4, v3
	v_fma_f32 v6, -v2, v5, v4
	v_fmac_f32_e32 v5, v6, v3
	v_fma_f32 v2, -v2, v5, v4
	v_div_fmas_f32 v2, v2, v3, v5
	v_div_fixup_f32 v1, v2, v1, 1.0
	v_div_scale_f32 v2, s[22:23], v0, v0, 1.0
	v_rcp_f32_e32 v3, v2
	s_movk_i32 s22, 0xff80
	v_and_or_b32 v118, v83, s22, v85
	v_bfe_u32 v83, v82, 4, 2
	v_fma_f32 v4, -v2, v3, 1.0
	v_fmac_f32_e32 v3, v4, v3
	v_div_scale_f32 v4, vcc, 1.0, v0, 1.0
	v_mul_f32_e32 v5, v4, v3
	v_fma_f32 v6, -v2, v5, v4
	v_fmac_f32_e32 v5, v6, v3
	v_fma_f32 v2, -v2, v5, v4
	v_div_fmas_f32 v2, v2, v3, v5
	v_ashrrev_i32_e32 v4, 3, v82
	v_div_fixup_f32 v0, v2, v0, 1.0
	v_add_u32_e32 v2, s20, v4
	v_ashrrev_i32_e32 v3, 31, v2
	v_cvt_pk_bf16_f32 v81, v0, v1
	v_lshl_add_u64 v[0:1], s[4:5], 0, v[130:131]
	v_lshlrev_b64 v[2:3], 9, v[2:3]
	v_lshl_add_u64 v[40:41], v[0:1], 0, v[2:3]
	v_add_u32_e32 v0, s19, v4
	v_ashrrev_i32_e32 v1, 31, v0
	v_lshlrev_b64 v[0:1], 11, v[0:1]
	v_lshl_add_u64 v[0:1], s[0:1], 0, v[0:1]
	v_lshl_add_u64 v[42:43], v[0:1], 0, v[130:131]
	v_add_co_u32_e32 v44, vcc, s33, v42
	global_load_dwordx4 v[20:23], v[42:43], off
	s_nop 0
	v_addc_co_u32_e32 v45, vcc, 0, v43, vcc
	v_add_co_u32_e32 v46, vcc, s56, v42
	global_load_dwordx4 v[24:27], v[44:45], off
	s_nop 0
	v_addc_co_u32_e32 v47, vcc, 0, v43, vcc
	global_load_dwordx4 v[28:31], v[46:47], off
	v_add_co_u32_e32 v48, vcc, s57, v42
	v_lshlrev_b32_e32 v85, 5, v82
	s_nop 0
	v_addc_co_u32_e32 v49, vcc, 0, v43, vcc
	global_load_dwordx4 v[32:35], v[48:49], off
	global_load_dwordx4 v[36:39], v[40:41], off
	global_load_dwordx4 v[0:3], v[42:43], off offset:128
	global_load_dwordx4 v[4:7], v[44:45], off offset:128
	global_load_dwordx4 v[8:11], v[46:47], off offset:128
	global_load_dwordx4 v[12:15], v[48:49], off offset:128
	global_load_dwordx4 v[16:19], v[40:41], off offset:128
	s_barrier
	s_waitcnt vmcnt(9)
	ds_write_b128 v118, v[20:23]
	s_waitcnt vmcnt(8)
	ds_write_b128 v118, v[24:27] offset:4096
	s_waitcnt vmcnt(7)
	ds_write_b128 v118, v[28:31] offset:8192
	s_waitcnt vmcnt(6)
	ds_write_b128 v118, v[32:35] offset:12288
	s_waitcnt vmcnt(5)
	ds_write_b128 v118, v[36:39] offset:16384
	s_waitcnt lgkmcnt(0)
	s_barrier
; #define GLOAD(ra, rb, koff)                                                        \
;   {                                                                                \
;     _Pragma("unroll") for (int j = 0; j < 4; j++) ra[j] = *(const u32x4*)(pa + j * sa32 + (koff));   \
;     _Pragma("unroll") for (int j = 0; j < NB_; j++) rb[j] = *(const u32x4*)(pbv[j] + (koff));         \
;   }
; template <int NT, bool PRE> ...
;     ...
;   if (!PRE) {
;     GLOAD(ra0, rb0, 0);
;     GLOAD(ra1, rb1, 64);
;   }
;   __syncthreads();
;   for (int k0 = 0; k0 < K; k0 += 128) {
;     LSTORE(ra0, rb0, 0);
;     __syncthreads();
;     GLOAD(ra0, rb0, min(k0 + 128, K - 128));
;     __builtin_amdgcn_sched_barrier(0);
;     COMPUTE(0);
;     LSTORE(ra1, rb1, 1);
;     __syncthreads();
;     GLOAD(ra1, rb1, min(k0 + 192, K - 64));
;     __builtin_amdgcn_sched_barrier(0);
;     COMPUTE(1);
; __device__ __forceinline__ void phase_merge(const Params& P, u16* sA, u16* sB) {
;     ...
;     for (int i = 0; i < 4; i++) {
;       f32x4 ap[4][1];
;       zero_acc<1>(ap);
;       gemm_main<1>(Y + i * 256, 1024, (const u16*)(ws + O_WB) + (size_t)i * 1024 * 256, 256, 256, m0, n0, ap, sA, sB);
	global_load_dwordx4 v[20:23], v[42:43], off offset:256
	global_load_dwordx4 v[24:27], v[44:45], off offset:256
	global_load_dwordx4 v[28:31], v[46:47], off offset:256
	global_load_dwordx4 v[32:35], v[48:49], off offset:256
	global_load_dwordx4 v[36:39], v[40:41], off offset:256
	v_lshlrev_b32_e32 v82, 6, v82
	v_bitop3_b32 v83, v83, v87, 4 bitop3:0x36
	v_and_or_b32 v85, v85, s21, v86
	v_and_b32_e32 v82, 0xffffe000, v82
	v_lshlrev_b32_e32 v83, 4, v83
	v_or3_b32 v119, v84, v82, v86
	v_or_b32_e32 v120, v85, v84
	v_or3_b32 v121, v83, v82, v86
	v_or_b32_e32 v122, v85, v83
	ds_read_b128 v[82:85], v119
	ds_read_b128 v[86:89], v119 offset:2048
	ds_read_b128 v[90:93], v119 offset:4096
	ds_read_b128 v[94:97], v119 offset:6144
	ds_read_b128 v[98:101], v120 offset:16384
	s_setprio 1
	s_waitcnt lgkmcnt(0)
	v_mfma_f32_16x16x32_bf16 v[82:85], v[98:101], v[82:85], 0
	v_mfma_f32_16x16x32_bf16 v[86:89], v[98:101], v[86:89], 0
	v_mfma_f32_16x16x32_bf16 v[90:93], v[98:101], v[90:93], 0
	v_mfma_f32_16x16x32_bf16 v[94:97], v[98:101], v[94:97], 0
	s_setprio 0
	ds_read_b128 v[98:101], v121
	ds_read_b128 v[102:105], v121 offset:2048
	ds_read_b128 v[106:109], v121 offset:4096
	ds_read_b128 v[110:113], v121 offset:6144
	ds_read_b128 v[114:117], v122 offset:16384
	s_setprio 1
	s_waitcnt lgkmcnt(0)
	v_mfma_f32_16x16x32_bf16 v[82:85], v[114:117], v[98:101], v[82:85]
	v_mfma_f32_16x16x32_bf16 v[86:89], v[114:117], v[102:105], v[86:89]
	v_mfma_f32_16x16x32_bf16 v[90:93], v[114:117], v[106:109], v[90:93]
	v_mfma_f32_16x16x32_bf16 v[94:97], v[114:117], v[110:113], v[94:97]
	s_setprio 0
	s_waitcnt vmcnt(9)
	ds_write_b128 v118, v[0:3] offset:32768
	s_waitcnt vmcnt(8)
	ds_write_b128 v118, v[4:7] offset:36864
	s_waitcnt vmcnt(7)
	ds_write_b128 v118, v[8:11] offset:40960
	s_waitcnt vmcnt(6)
	ds_write_b128 v118, v[12:15] offset:45056
	s_waitcnt vmcnt(5)
	ds_write_b128 v118, v[16:19] offset:49152
	s_waitcnt lgkmcnt(0)
	s_barrier
	global_load_dwordx4 v[0:3], v[44:45], off offset:384
	global_load_dwordx4 v[4:7], v[46:47], off offset:384
	global_load_dwordx4 v[8:11], v[48:49], off offset:384
	global_load_dwordx4 v[12:15], v[42:43], off offset:384
	global_load_dwordx4 v[16:19], v[40:41], off offset:384
	ds_read_b128 v[40:43], v119 offset:32768
	ds_read_b128 v[44:47], v119 offset:34816
	ds_read_b128 v[98:101], v119 offset:36864
	ds_read_b128 v[102:105], v119 offset:38912
	ds_read_b128 v[106:109], v120 offset:49152
	s_setprio 1
	s_waitcnt lgkmcnt(0)
	v_mfma_f32_16x16x32_bf16 v[40:43], v[106:109], v[40:43], v[82:85]
	v_mfma_f32_16x16x32_bf16 v[44:47], v[106:109], v[44:47], v[86:89]
	v_mfma_f32_16x16x32_bf16 v[82:85], v[106:109], v[98:101], v[90:93]
	v_mfma_f32_16x16x32_bf16 v[86:89], v[106:109], v[102:105], v[94:97]
	s_setprio 0
	s_nop 0
	ds_read_b128 v[90:93], v121 offset:32768
	ds_read_b128 v[94:97], v121 offset:34816
	ds_read_b128 v[98:101], v121 offset:36864
	ds_read_b128 v[102:105], v121 offset:38912
	ds_read_b128 v[106:109], v122 offset:49152
	s_setprio 1
	s_waitcnt lgkmcnt(0)
	v_mfma_f32_16x16x32_bf16 v[40:43], v[106:109], v[90:93], v[40:43]
	v_mfma_f32_16x16x32_bf16 v[44:47], v[106:109], v[94:97], v[44:47]
	v_mfma_f32_16x16x32_bf16 v[82:85], v[106:109], v[98:101], v[82:85]
	v_mfma_f32_16x16x32_bf16 v[86:89], v[106:109], v[102:105], v[86:89]
	s_setprio 0
	s_waitcnt vmcnt(9)
	ds_write_b128 v118, v[20:23]
	s_waitcnt vmcnt(8)
	ds_write_b128 v118, v[24:27] offset:4096
	s_waitcnt vmcnt(7)
	ds_write_b128 v118, v[28:31] offset:8192
	s_waitcnt vmcnt(6)
	ds_write_b128 v118, v[32:35] offset:12288
	s_waitcnt vmcnt(5)
	ds_write_b128 v118, v[36:39] offset:16384
	s_waitcnt lgkmcnt(0)
	s_barrier
	ds_read_b128 v[20:23], v119
	ds_read_b128 v[24:27], v119 offset:2048
	ds_read_b128 v[28:31], v119 offset:4096
	ds_read_b128 v[32:35], v119 offset:6144
	ds_read_b128 v[36:39], v120 offset:16384
	s_setprio 1
	s_waitcnt lgkmcnt(0)
	v_mfma_f32_16x16x32_bf16 v[20:23], v[36:39], v[20:23], v[40:43]
	v_mfma_f32_16x16x32_bf16 v[24:27], v[36:39], v[24:27], v[44:47]
	v_mfma_f32_16x16x32_bf16 v[28:31], v[36:39], v[28:31], v[82:85]
	v_mfma_f32_16x16x32_bf16 v[32:35], v[36:39], v[32:35], v[86:89]
	s_setprio 0
	ds_read_b128 v[36:39], v121
	ds_read_b128 v[40:43], v121 offset:2048
	ds_read_b128 v[44:47], v121 offset:4096
	ds_read_b128 v[82:85], v121 offset:6144
	ds_read_b128 v[86:89], v122 offset:16384
	s_setprio 1
	s_waitcnt lgkmcnt(0)
	v_mfma_f32_16x16x32_bf16 v[20:23], v[86:89], v[36:39], v[20:23]
	v_mfma_f32_16x16x32_bf16 v[24:27], v[86:89], v[40:43], v[24:27]
	v_mfma_f32_16x16x32_bf16 v[28:31], v[86:89], v[44:47], v[28:31]
	v_mfma_f32_16x16x32_bf16 v[32:35], v[86:89], v[82:85], v[32:35]
	s_setprio 0
	s_waitcnt vmcnt(1)
	ds_write_b128 v118, v[12:15] offset:32768
	ds_write_b128 v118, v[0:3] offset:36864
	ds_write_b128 v118, v[4:7] offset:40960
	ds_write_b128 v118, v[8:11] offset:45056
	s_waitcnt vmcnt(0)
	ds_write_b128 v118, v[16:19] offset:49152
	s_waitcnt lgkmcnt(0)
	s_barrier
; #define GLOAD(ra, rb, koff)                                                        \
;   {                                                                                \
;     _Pragma("unroll") for (int j = 0; j < 4; j++) ra[j] = *(const u32x4*)(pa + j * sa32 + (koff));   \
;     _Pragma("unroll") for (int j = 0; j < NB_; j++) rb[j] = *(const u32x4*)(pbv[j] + (koff));         \
;   }
; template <int NT, bool PRE> ...
;     ...
;   if (!PRE) {
;     GLOAD(ra0, rb0, 0);
;     GLOAD(ra1, rb1, 64);
;   }
;   __syncthreads();
;   for (int k0 = 0; k0 < K; k0 += 128) {
;     LSTORE(ra0, rb0, 0);
;     __syncthreads();
;     GLOAD(ra0, rb0, min(k0 + 128, K - 128));
;     __builtin_amdgcn_sched_barrier(0);
;     COMPUTE(0);
;     LSTORE(ra1, rb1, 1);
;     __syncthreads();
;     GLOAD(ra1, rb1, min(k0 + 192, K - 64));
;     __builtin_amdgcn_sched_barrier(0);
;     COMPUTE(1);
; __device__ __forceinline__ void phase_merge(const Params& P, u16* sA, u16* sB) {
;     ...
;     for (int i = 0; i < 4; i++) {
;       f32x4 ap[4][1];
;       zero_acc<1>(ap);
;       gemm_main<1>(Y + i * 256, 1024, (const u16*)(ws + O_WB) + (size_t)i * 1024 * 256, 256, 256, m0, n0, ap, sA, sB);
	ds_read_b128 v[0:3], v119 offset:32768
	ds_read_b128 v[4:7], v119 offset:34816
	ds_read_b128 v[8:11], v119 offset:36864
	ds_read_b128 v[12:15], v119 offset:38912
	ds_read_b128 v[16:19], v120 offset:49152
	s_setprio 1
	s_waitcnt lgkmcnt(0)
	v_mfma_f32_16x16x32_bf16 v[0:3], v[16:19], v[0:3], v[20:23]
	v_mfma_f32_16x16x32_bf16 v[4:7], v[16:19], v[4:7], v[24:27]
	v_mfma_f32_16x16x32_bf16 v[20:23], v[16:19], v[8:11], v[28:31]
	v_mfma_f32_16x16x32_bf16 v[16:19], v[16:19], v[12:15], v[32:35]
	s_setprio 0
	ds_read_b128 v[8:11], v121 offset:32768
	ds_read_b128 v[24:27], v121 offset:34816
	ds_read_b128 v[28:31], v121 offset:36864
	ds_read_b128 v[32:35], v121 offset:38912
	ds_read_b128 v[36:39], v122 offset:49152
	s_setprio 1
	s_waitcnt lgkmcnt(0)
	v_mfma_f32_16x16x32_bf16 v[12:15], v[36:39], v[8:11], v[0:3]
	v_mfma_f32_16x16x32_bf16 v[8:11], v[36:39], v[24:27], v[4:7]
	v_mfma_f32_16x16x32_bf16 v[4:7], v[36:39], v[28:31], v[20:23]
	v_mfma_f32_16x16x32_bf16 v[0:3], v[36:39], v[32:35], v[16:19]
	s_setprio 0
	v_mov_b32_e32 v90, v169
	s_nop 0
	v_ashrrev_i32_e32 v20, 3, v90
	v_lshlrev_b32_e32 v36, 4, v90
	v_add_u32_e32 v18, s20, v20
	v_and_b32_e32 v130, 0x70, v36
	v_ashrrev_i32_e32 v19, 31, v18
	v_lshl_add_u64 v[16:17], s[8:9], 0, v[130:131]
	v_lshlrev_b64 v[18:19], 9, v[18:19]
	v_lshl_add_u64 v[48:49], v[16:17], 0, v[18:19]
	v_add_u32_e32 v16, s19, v20
	v_ashrrev_i32_e32 v17, 31, v16
	v_lshlrev_b64 v[16:17], 11, v[16:17]
	v_lshl_add_u64 v[16:17], s[6:7], 0, v[16:17]
	v_lshl_add_u64 v[126:127], v[16:17], 0, v[130:131]
	v_add_co_u32_e32 v136, vcc, s33, v126
	global_load_dwordx4 v[16:19], v[126:127], off
	s_nop 0
	v_addc_co_u32_e32 v137, vcc, 0, v127, vcc
	v_add_co_u32_e32 v138, vcc, s56, v126
	global_load_dwordx4 v[20:23], v[136:137], off
	s_nop 0
	v_addc_co_u32_e32 v139, vcc, 0, v127, vcc
	global_load_dwordx4 v[24:27], v[138:139], off
	global_load_dwordx4 v[28:31], v[48:49], off
	v_add_co_u32_e32 v140, vcc, s57, v126
	v_lshrrev_b32_e32 v91, 4, v90
	s_nop 0
	v_addc_co_u32_e32 v141, vcc, 0, v127, vcc
	global_load_dwordx4 v[32:35], v[140:141], off
	v_xor_b32_e32 v37, v91, v90
	v_lshlrev_b32_e32 v37, 4, v37
	v_and_b32_e32 v37, 0x70, v37
	v_and_or_b32 v130, v36, s22, v37
	global_load_dwordx4 v[36:39], v[48:49], off offset:128
	global_load_dwordx4 v[40:43], v[126:127], off offset:128
	global_load_dwordx4 v[44:47], v[136:137], off offset:128
	global_load_dwordx4 v[82:85], v[138:139], off offset:128
	global_load_dwordx4 v[86:89], v[140:141], off offset:128
	s_barrier
	v_and_b32_e32 v92, 15, v90
	v_bfe_u32 v93, v90, 1, 3
	v_bfe_u32 v94, v90, 4, 2
	v_lshlrev_b32_e32 v95, 5, v90
	v_lshlrev_b32_e32 v92, 7, v92
	v_bitop3_b32 v91, v91, v93, 3 bitop3:0x6c
	v_lshlrev_b32_e32 v90, 6, v90
	v_and_or_b32 v95, v95, s21, v92
	v_lshlrev_b32_e32 v91, 4, v91
	v_and_b32_e32 v90, 0xffffe000, v90
	v_or3_b32 v142, v91, v90, v92
	v_or_b32_e32 v143, v95, v91
	v_bitop3_b32 v91, v94, v93, 4 bitop3:0x36
	v_lshlrev_b32_e32 v91, 4, v91
	v_or3_b32 v144, v91, v90, v92
	v_or_b32_e32 v145, v95, v91
	s_waitcnt vmcnt(6)
	ds_write_b128 v130, v[28:31] offset:16384
	ds_write_b128 v130, v[16:19]
	ds_write_b128 v130, v[20:23] offset:4096
	ds_write_b128 v130, v[24:27] offset:8192
	s_waitcnt vmcnt(5)
	ds_write_b128 v130, v[32:35] offset:12288
	s_waitcnt lgkmcnt(0)
	s_barrier
	global_load_dwordx4 v[16:19], v[136:137], off offset:256
	global_load_dwordx4 v[20:23], v[138:139], off offset:256
	global_load_dwordx4 v[24:27], v[140:141], off offset:256
	global_load_dwordx4 v[28:31], v[126:127], off offset:256
	global_load_dwordx4 v[32:35], v[48:49], off offset:256
	ds_read_b128 v[90:93], v142
	ds_read_b128 v[94:97], v142 offset:2048
	ds_read_b128 v[98:101], v142 offset:4096
	ds_read_b128 v[102:105], v142 offset:6144
	ds_read_b128 v[106:109], v143 offset:16384
	s_setprio 1
	s_waitcnt lgkmcnt(0)
	v_mfma_f32_16x16x32_bf16 v[90:93], v[106:109], v[90:93], 0
	v_mfma_f32_16x16x32_bf16 v[94:97], v[106:109], v[94:97], 0
	v_mfma_f32_16x16x32_bf16 v[98:101], v[106:109], v[98:101], 0
	v_mfma_f32_16x16x32_bf16 v[102:105], v[106:109], v[102:105], 0
	s_setprio 0
	ds_read_b128 v[106:109], v144
	ds_read_b128 v[110:113], v144 offset:2048
	ds_read_b128 v[114:117], v144 offset:4096
	ds_read_b128 v[118:121], v144 offset:6144
	ds_read_b128 v[122:125], v145 offset:16384
	s_setprio 1
	s_waitcnt lgkmcnt(0)
	v_mfma_f32_16x16x32_bf16 v[90:93], v[122:125], v[106:109], v[90:93]
	v_mfma_f32_16x16x32_bf16 v[94:97], v[122:125], v[110:113], v[94:97]
	v_mfma_f32_16x16x32_bf16 v[98:101], v[122:125], v[114:117], v[98:101]
	v_mfma_f32_16x16x32_bf16 v[102:105], v[122:125], v[118:121], v[102:105]
	s_setprio 0
	s_waitcnt vmcnt(8)
	ds_write_b128 v130, v[40:43] offset:32768
	s_waitcnt vmcnt(7)
	ds_write_b128 v130, v[44:47] offset:36864
	s_waitcnt vmcnt(6)
	ds_write_b128 v130, v[82:85] offset:40960
	s_waitcnt vmcnt(5)
	ds_write_b128 v130, v[86:89] offset:45056
	ds_write_b128 v130, v[36:39] offset:49152
	s_waitcnt lgkmcnt(0)
	s_barrier
; #define GLOAD(ra, rb, koff)                                                        \
;   {                                                                                \
;     _Pragma("unroll") for (int j = 0; j < 4; j++) ra[j] = *(const u32x4*)(pa + j * sa32 + (koff));   \
;     _Pragma("unroll") for (int j = 0; j < NB_; j++) rb[j] = *(const u32x4*)(pbv[j] + (koff));         \
;   }
; template <int NT, bool PRE> ...
;     ...
;   if (!PRE) {
;     GLOAD(ra0, rb0, 0);
;     GLOAD(ra1, rb1, 64);
;   }
;   __syncthreads();
;   for (int k0 = 0; k0 < K; k0 += 128) {
;     LSTORE(ra0, rb0, 0);
;     __syncthreads();
;     GLOAD(ra0, rb0, min(k0 + 128, K - 128));
;     __builtin_amdgcn_sched_barrier(0);
;     COMPUTE(0);
;     LSTORE(ra1, rb1, 1);
;     __syncthreads();
;     GLOAD(ra1, rb1, min(k0 + 192, K - 64));
;     __builtin_amdgcn_sched_barrier(0);
;     COMPUTE(1);
; __device__ __forceinline__ void phase_merge(const Params& P, u16* sA, u16* sB) {
;     ...
;     for (int i = 0; i < 4; i++) {
;       f32x4 ap[4][1];
;       zero_acc<1>(ap);
;       gemm_main<1>(Y + i * 256, 1024, (const u16*)(ws + O_WB) + (size_t)i * 1024 * 256, 256, 256, m0, n0, ap, sA, sB);
	global_load_dwordx4 v[36:39], v[136:137], off offset:384
	global_load_dwordx4 v[40:43], v[138:139], off offset:384
	global_load_dwordx4 v[44:47], v[140:141], off offset:384
	global_load_dwordx4 v[82:85], v[126:127], off offset:384
	global_load_dwordx4 v[86:89], v[48:49], off offset:384
	ds_read_b128 v[106:109], v142 offset:32768
	ds_read_b128 v[110:113], v142 offset:34816
	ds_read_b128 v[114:117], v142 offset:36864
	ds_read_b128 v[118:121], v142 offset:38912
	ds_read_b128 v[122:125], v143 offset:49152
	s_setprio 1
	s_waitcnt lgkmcnt(0)
	v_mfma_f32_16x16x32_bf16 v[90:93], v[122:125], v[106:109], v[90:93]
	v_mfma_f32_16x16x32_bf16 v[94:97], v[122:125], v[110:113], v[94:97]
	v_mfma_f32_16x16x32_bf16 v[98:101], v[122:125], v[114:117], v[98:101]
	v_mfma_f32_16x16x32_bf16 v[102:105], v[122:125], v[118:121], v[102:105]
	s_setprio 0
	ds_read_b128 v[106:109], v144 offset:32768
	ds_read_b128 v[110:113], v144 offset:34816
	ds_read_b128 v[114:117], v144 offset:36864
	ds_read_b128 v[118:121], v144 offset:38912
	ds_read_b128 v[122:125], v145 offset:49152
	s_setprio 1
	s_waitcnt lgkmcnt(0)
	v_mfma_f32_16x16x32_bf16 v[90:93], v[122:125], v[106:109], v[90:93]
	v_mfma_f32_16x16x32_bf16 v[94:97], v[122:125], v[110:113], v[94:97]
	v_mfma_f32_16x16x32_bf16 v[98:101], v[122:125], v[114:117], v[98:101]
	v_mfma_f32_16x16x32_bf16 v[102:105], v[122:125], v[118:121], v[102:105]
	s_setprio 0
	s_waitcnt vmcnt(6)
	ds_write_b128 v130, v[28:31]
	ds_write_b128 v130, v[16:19] offset:4096
	ds_write_b128 v130, v[20:23] offset:8192
	ds_write_b128 v130, v[24:27] offset:12288
	s_waitcnt vmcnt(5)
	ds_write_b128 v130, v[32:35] offset:16384
	s_waitcnt lgkmcnt(0)
	s_barrier
	ds_read_b128 v[16:19], v142
	ds_read_b128 v[20:23], v142 offset:2048
	ds_read_b128 v[24:27], v142 offset:4096
	ds_read_b128 v[28:31], v142 offset:6144
	ds_read_b128 v[32:35], v143 offset:16384
	s_setprio 1
	s_waitcnt lgkmcnt(0)
	v_mfma_f32_16x16x32_bf16 v[16:19], v[32:35], v[16:19], v[90:93]
	v_mfma_f32_16x16x32_bf16 v[20:23], v[32:35], v[20:23], v[94:97]
	v_mfma_f32_16x16x32_bf16 v[24:27], v[32:35], v[24:27], v[98:101]
	v_mfma_f32_16x16x32_bf16 v[28:31], v[32:35], v[28:31], v[102:105]
	s_setprio 0
	ds_read_b128 v[32:35], v144
	ds_read_b128 v[90:93], v144 offset:2048
	ds_read_b128 v[94:97], v144 offset:4096
	ds_read_b128 v[98:101], v144 offset:6144
	ds_read_b128 v[102:105], v145 offset:16384
	s_setprio 1
	s_waitcnt lgkmcnt(0)
	v_mfma_f32_16x16x32_bf16 v[16:19], v[102:105], v[32:35], v[16:19]
	v_mfma_f32_16x16x32_bf16 v[20:23], v[102:105], v[90:93], v[20:23]
	v_mfma_f32_16x16x32_bf16 v[24:27], v[102:105], v[94:97], v[24:27]
	v_mfma_f32_16x16x32_bf16 v[28:31], v[102:105], v[98:101], v[28:31]
	s_setprio 0
	s_waitcnt vmcnt(1)
	ds_write_b128 v130, v[82:85] offset:32768
	ds_write_b128 v130, v[36:39] offset:36864
	ds_write_b128 v130, v[40:43] offset:40960
	ds_write_b128 v130, v[44:47] offset:45056
	s_waitcnt vmcnt(0)
	ds_write_b128 v130, v[86:89] offset:49152
	s_waitcnt lgkmcnt(0)
	s_barrier
	ds_read_b128 v[32:35], v142 offset:32768
	ds_read_b128 v[36:39], v142 offset:34816
	ds_read_b128 v[40:43], v142 offset:36864
	ds_read_b128 v[44:47], v142 offset:38912
	ds_read_b128 v[82:85], v143 offset:49152
	s_setprio 1
	s_waitcnt lgkmcnt(0)
	v_mfma_f32_16x16x32_bf16 v[16:19], v[82:85], v[32:35], v[16:19]
	v_mfma_f32_16x16x32_bf16 v[20:23], v[82:85], v[36:39], v[20:23]
	v_mfma_f32_16x16x32_bf16 v[32:35], v[82:85], v[40:43], v[24:27]
	v_mfma_f32_16x16x32_bf16 v[36:39], v[82:85], v[44:47], v[28:31]
	s_setprio 0
	s_nop 0
	ds_read_b128 v[24:27], v144 offset:32768
	ds_read_b128 v[40:43], v144 offset:34816
	ds_read_b128 v[44:47], v144 offset:36864
	ds_read_b128 v[82:85], v144 offset:38912
	ds_read_b128 v[86:89], v145 offset:49152
	s_setprio 1
	s_waitcnt lgkmcnt(0)
	v_mfma_f32_16x16x32_bf16 v[28:31], v[86:89], v[24:27], v[16:19]
	v_mfma_f32_16x16x32_bf16 v[24:27], v[86:89], v[40:43], v[20:23]
	v_mfma_f32_16x16x32_bf16 v[20:23], v[86:89], v[44:47], v[32:35]
	v_mfma_f32_16x16x32_bf16 v[16:19], v[86:89], v[82:85], v[36:39]
	s_setprio 0
	v_mov_b32_e32 v106, v169
	s_nop 0
	v_ashrrev_i32_e32 v36, 3, v106
	v_lshlrev_b32_e32 v86, 4, v106
	v_add_u32_e32 v34, s20, v36
	v_and_b32_e32 v130, 0x70, v86
	v_ashrrev_i32_e32 v35, 31, v34
	v_lshl_add_u64 v[32:33], s[12:13], 0, v[130:131]
	v_lshlrev_b64 v[34:35], 9, v[34:35]
	v_lshl_add_u64 v[48:49], v[32:33], 0, v[34:35]
	v_add_u32_e32 v32, s19, v36
	v_ashrrev_i32_e32 v33, 31, v32
	v_lshlrev_b64 v[32:33], 11, v[32:33]
	v_lshl_add_u64 v[32:33], s[10:11], 0, v[32:33]
	v_lshl_add_u64 v[126:127], v[32:33], 0, v[130:131]
	v_add_co_u32_e32 v144, vcc, s33, v126
	global_load_dwordx4 v[32:35], v[126:127], off
	s_nop 0
	v_addc_co_u32_e32 v145, vcc, 0, v127, vcc
	v_add_co_u32_e32 v166, vcc, s56, v126
	global_load_dwordx4 v[36:39], v[144:145], off
	s_nop 0
	v_addc_co_u32_e32 v167, vcc, 0, v127, vcc
	global_load_dwordx4 v[40:43], v[166:167], off
	global_load_dwordx4 v[44:47], v[48:49], off
	v_add_co_u32_e32 v198, vcc, s57, v126
	v_lshrrev_b32_e32 v107, 4, v106
	s_nop 0
	v_addc_co_u32_e32 v199, vcc, 0, v127, vcc
	global_load_dwordx4 v[82:85], v[198:199], off
	v_xor_b32_e32 v87, v107, v106
	v_lshlrev_b32_e32 v87, 4, v87
	v_and_b32_e32 v87, 0x70, v87
	v_and_or_b32 v130, v86, s22, v87
	global_load_dwordx4 v[86:89], v[48:49], off offset:128
	global_load_dwordx4 v[90:93], v[126:127], off offset:128
	global_load_dwordx4 v[94:97], v[144:145], off offset:128
	global_load_dwordx4 v[98:101], v[166:167], off offset:128
	global_load_dwordx4 v[102:105], v[198:199], off offset:128
	s_barrier
; #define GLOAD(ra, rb, koff)                                                        \
;   {                                                                                \
;     _Pragma("unroll") for (int j = 0; j < 4; j++) ra[j] = *(const u32x4*)(pa + j * sa32 + (koff));   \
;     _Pragma("unroll") for (int j = 0; j < NB_; j++) rb[j] = *(const u32x4*)(pbv[j] + (koff));         \
;   }
; template <int NT, bool PRE> ...
;     ...
;   if (!PRE) {
;     GLOAD(ra0, rb0, 0);
;     GLOAD(ra1, rb1, 64);
;   }
;   __syncthreads();
;   for (int k0 = 0; k0 < K; k0 += 128) {
;     LSTORE(ra0, rb0, 0);
;     __syncthreads();
;     GLOAD(ra0, rb0, min(k0 + 128, K - 128));
;     __builtin_amdgcn_sched_barrier(0);
;     COMPUTE(0);
;     LSTORE(ra1, rb1, 1);
;     __syncthreads();
;     GLOAD(ra1, rb1, min(k0 + 192, K - 64));
;     __builtin_amdgcn_sched_barrier(0);
;     COMPUTE(1);
; __device__ __forceinline__ void phase_merge(const Params& P, u16* sA, u16* sB) {
;     ...
;     for (int i = 0; i < 4; i++) {
;       f32x4 ap[4][1];
;       zero_acc<1>(ap);
;       gemm_main<1>(Y + i * 256, 1024, (const u16*)(ws + O_WB) + (size_t)i * 1024 * 256, 256, 256, m0, n0, ap, sA, sB);
	v_and_b32_e32 v108, 15, v106
	v_bfe_u32 v109, v106, 1, 3
	v_bfe_u32 v110, v106, 4, 2
	v_lshlrev_b32_e32 v111, 5, v106
	v_lshlrev_b32_e32 v108, 7, v108
	v_bitop3_b32 v107, v107, v109, 3 bitop3:0x6c
	v_lshlrev_b32_e32 v106, 6, v106
	v_and_or_b32 v111, v111, s21, v108
	v_lshlrev_b32_e32 v107, 4, v107
	v_and_b32_e32 v106, 0xffffe000, v106
	v_or3_b32 v157, v107, v106, v108
	v_or_b32_e32 v168, v111, v107
	v_bitop3_b32 v107, v110, v109, 4 bitop3:0x36
	v_lshlrev_b32_e32 v107, 4, v107
	v_or3_b32 v197, v107, v106, v108
	v_or_b32_e32 v200, v111, v107
	s_waitcnt vmcnt(6)
	ds_write_b128 v130, v[44:47] offset:16384
	ds_write_b128 v130, v[32:35]
	ds_write_b128 v130, v[36:39] offset:4096
	ds_write_b128 v130, v[40:43] offset:8192
	s_waitcnt vmcnt(5)
	ds_write_b128 v130, v[82:85] offset:12288
	s_waitcnt lgkmcnt(0)
	s_barrier
	global_load_dwordx4 v[32:35], v[144:145], off offset:256
	global_load_dwordx4 v[36:39], v[166:167], off offset:256
	global_load_dwordx4 v[40:43], v[198:199], off offset:256
	global_load_dwordx4 v[44:47], v[126:127], off offset:256
	global_load_dwordx4 v[82:85], v[48:49], off offset:256
	ds_read_b128 v[106:109], v157
	ds_read_b128 v[110:113], v157 offset:2048
	ds_read_b128 v[114:117], v157 offset:4096
	ds_read_b128 v[118:121], v157 offset:6144
	ds_read_b128 v[122:125], v168 offset:16384
	s_setprio 1
	s_waitcnt lgkmcnt(0)
	v_mfma_f32_16x16x32_bf16 v[106:109], v[122:125], v[106:109], 0
	v_mfma_f32_16x16x32_bf16 v[110:113], v[122:125], v[110:113], 0
	v_mfma_f32_16x16x32_bf16 v[114:117], v[122:125], v[114:117], 0
	v_mfma_f32_16x16x32_bf16 v[118:121], v[122:125], v[118:121], 0
	s_setprio 0
	ds_read_b128 v[122:125], v197
	ds_read_b128 v[136:139], v197 offset:2048
	ds_read_b128 v[140:143], v197 offset:4096
	ds_read_b128 v[158:161], v197 offset:6144
	ds_read_b128 v[162:165], v200 offset:16384
	s_setprio 1
	s_waitcnt lgkmcnt(0)
	v_mfma_f32_16x16x32_bf16 v[106:109], v[162:165], v[122:125], v[106:109]
	v_mfma_f32_16x16x32_bf16 v[110:113], v[162:165], v[136:139], v[110:113]
	v_mfma_f32_16x16x32_bf16 v[114:117], v[162:165], v[140:143], v[114:117]
	v_mfma_f32_16x16x32_bf16 v[118:121], v[162:165], v[158:161], v[118:121]
	s_setprio 0
	s_waitcnt vmcnt(8)
	ds_write_b128 v130, v[90:93] offset:32768
	s_waitcnt vmcnt(7)
	ds_write_b128 v130, v[94:97] offset:36864
	s_waitcnt vmcnt(6)
	ds_write_b128 v130, v[98:101] offset:40960
	s_waitcnt vmcnt(5)
	ds_write_b128 v130, v[102:105] offset:45056
	ds_write_b128 v130, v[86:89] offset:49152
	s_waitcnt lgkmcnt(0)
	s_barrier
	global_load_dwordx4 v[86:89], v[144:145], off offset:384
	global_load_dwordx4 v[90:93], v[166:167], off offset:384
	global_load_dwordx4 v[94:97], v[198:199], off offset:384
	global_load_dwordx4 v[98:101], v[126:127], off offset:384
	global_load_dwordx4 v[102:105], v[48:49], off offset:384
	ds_read_b128 v[122:125], v157 offset:32768
	ds_read_b128 v[136:139], v157 offset:34816
	ds_read_b128 v[140:143], v157 offset:36864
	ds_read_b128 v[158:161], v157 offset:38912
	ds_read_b128 v[162:165], v168 offset:49152
	s_setprio 1
	s_waitcnt lgkmcnt(0)
	v_mfma_f32_16x16x32_bf16 v[106:109], v[162:165], v[122:125], v[106:109]
	v_mfma_f32_16x16x32_bf16 v[110:113], v[162:165], v[136:139], v[110:113]
	v_mfma_f32_16x16x32_bf16 v[114:117], v[162:165], v[140:143], v[114:117]
	v_mfma_f32_16x16x32_bf16 v[118:121], v[162:165], v[158:161], v[118:121]
	s_setprio 0
	ds_read_b128 v[122:125], v197 offset:32768
	ds_read_b128 v[136:139], v197 offset:34816
	ds_read_b128 v[140:143], v197 offset:36864
	ds_read_b128 v[158:161], v197 offset:38912
	ds_read_b128 v[162:165], v200 offset:49152
	s_setprio 1
	s_waitcnt lgkmcnt(0)
	v_mfma_f32_16x16x32_bf16 v[106:109], v[162:165], v[122:125], v[106:109]
	v_mfma_f32_16x16x32_bf16 v[110:113], v[162:165], v[136:139], v[110:113]
	v_mfma_f32_16x16x32_bf16 v[114:117], v[162:165], v[140:143], v[114:117]
	v_mfma_f32_16x16x32_bf16 v[118:121], v[162:165], v[158:161], v[118:121]
	s_setprio 0
	s_waitcnt vmcnt(6)
	ds_write_b128 v130, v[44:47]
	ds_write_b128 v130, v[32:35] offset:4096
	ds_write_b128 v130, v[36:39] offset:8192
	ds_write_b128 v130, v[40:43] offset:12288
	s_waitcnt vmcnt(5)
	ds_write_b128 v130, v[82:85] offset:16384
	s_waitcnt lgkmcnt(0)
	s_barrier
	ds_read_b128 v[32:35], v157
	ds_read_b128 v[36:39], v157 offset:2048
	ds_read_b128 v[40:43], v157 offset:4096
	ds_read_b128 v[44:47], v157 offset:6144
	ds_read_b128 v[82:85], v168 offset:16384
	s_setprio 1
	s_waitcnt lgkmcnt(0)
	v_mfma_f32_16x16x32_bf16 v[32:35], v[82:85], v[32:35], v[106:109]
	v_mfma_f32_16x16x32_bf16 v[36:39], v[82:85], v[36:39], v[110:113]
	v_mfma_f32_16x16x32_bf16 v[40:43], v[82:85], v[40:43], v[114:117]
	v_mfma_f32_16x16x32_bf16 v[44:47], v[82:85], v[44:47], v[118:121]
	s_setprio 0
	ds_read_b128 v[82:85], v197
	ds_read_b128 v[106:109], v197 offset:2048
	ds_read_b128 v[110:113], v197 offset:4096
	ds_read_b128 v[114:117], v197 offset:6144
	ds_read_b128 v[118:121], v200 offset:16384
	s_setprio 1
	s_waitcnt lgkmcnt(0)
	v_mfma_f32_16x16x32_bf16 v[32:35], v[118:121], v[82:85], v[32:35]
	v_mfma_f32_16x16x32_bf16 v[36:39], v[118:121], v[106:109], v[36:39]
	v_mfma_f32_16x16x32_bf16 v[40:43], v[118:121], v[110:113], v[40:43]
	v_mfma_f32_16x16x32_bf16 v[44:47], v[118:121], v[114:117], v[44:47]
	s_setprio 0
	s_waitcnt vmcnt(1)
	ds_write_b128 v130, v[98:101] offset:32768
	ds_write_b128 v130, v[86:89] offset:36864
	ds_write_b128 v130, v[90:93] offset:40960
	ds_write_b128 v130, v[94:97] offset:45056
	s_waitcnt vmcnt(0)
	ds_write_b128 v130, v[102:105] offset:49152
	s_waitcnt lgkmcnt(0)
	s_barrier
; #define GLOAD(ra, rb, koff)                                                        \
;   {                                                                                \
;     _Pragma("unroll") for (int j = 0; j < 4; j++) ra[j] = *(const u32x4*)(pa + j * sa32 + (koff));   \
;     _Pragma("unroll") for (int j = 0; j < NB_; j++) rb[j] = *(const u32x4*)(pbv[j] + (koff));         \
;   }
; template <int NT, bool PRE> ...
;     ...
;   if (!PRE) {
;     GLOAD(ra0, rb0, 0);
;     GLOAD(ra1, rb1, 64);
;   }
;   __syncthreads();
;   for (int k0 = 0; k0 < K; k0 += 128) {
;     LSTORE(ra0, rb0, 0);
;     __syncthreads();
;     GLOAD(ra0, rb0, min(k0 + 128, K - 128));
;     __builtin_amdgcn_sched_barrier(0);
;     COMPUTE(0);
;     LSTORE(ra1, rb1, 1);
;     __syncthreads();
;     GLOAD(ra1, rb1, min(k0 + 192, K - 64));
;     __builtin_amdgcn_sched_barrier(0);
;     COMPUTE(1);
; __device__ __forceinline__ void phase_merge(const Params& P, u16* sA, u16* sB) {
;     ...
;     for (int i = 0; i < 4; i++) {
;       f32x4 ap[4][1];
;       zero_acc<1>(ap);
;       gemm_main<1>(Y + i * 256, 1024, (const u16*)(ws + O_WB) + (size_t)i * 1024 * 256, 256, 256, m0, n0, ap, sA, sB);
	ds_read_b128 v[82:85], v157 offset:32768
	ds_read_b128 v[86:89], v157 offset:34816
	ds_read_b128 v[90:93], v157 offset:36864
	ds_read_b128 v[94:97], v157 offset:38912
	ds_read_b128 v[98:101], v168 offset:49152
	s_setprio 1
	s_waitcnt lgkmcnt(0)
	v_mfma_f32_16x16x32_bf16 v[32:35], v[98:101], v[82:85], v[32:35]
	v_mfma_f32_16x16x32_bf16 v[36:39], v[98:101], v[86:89], v[36:39]
	v_mfma_f32_16x16x32_bf16 v[82:85], v[98:101], v[90:93], v[40:43]
	v_mfma_f32_16x16x32_bf16 v[86:89], v[98:101], v[94:97], v[44:47]
	s_setprio 0
	s_nop 0
	ds_read_b128 v[40:43], v197 offset:32768
	ds_read_b128 v[90:93], v197 offset:34816
	ds_read_b128 v[94:97], v197 offset:36864
	ds_read_b128 v[98:101], v197 offset:38912
	ds_read_b128 v[102:105], v200 offset:49152
	s_setprio 1
	s_waitcnt lgkmcnt(0)
	v_mfma_f32_16x16x32_bf16 v[44:47], v[102:105], v[40:43], v[32:35]
	v_mfma_f32_16x16x32_bf16 v[40:43], v[102:105], v[90:93], v[36:39]
	v_mfma_f32_16x16x32_bf16 v[36:39], v[102:105], v[94:97], v[82:85]
	v_mfma_f32_16x16x32_bf16 v[32:35], v[102:105], v[98:101], v[86:89]
	s_setprio 0
	v_mov_b32_e32 v122, v169
	s_nop 0
	v_ashrrev_i32_e32 v84, 3, v122
	v_lshlrev_b32_e32 v102, 4, v122
	v_add_u32_e32 v82, s20, v84
	v_and_b32_e32 v130, 0x70, v102
	v_ashrrev_i32_e32 v83, 31, v82
	v_lshl_add_u64 v[48:49], s[16:17], 0, v[130:131]
	v_lshlrev_b64 v[82:83], 9, v[82:83]
	v_lshl_add_u64 v[48:49], v[48:49], 0, v[82:83]
	v_add_u32_e32 v82, s19, v84
	v_ashrrev_i32_e32 v83, 31, v82
	v_lshlrev_b64 v[82:83], 11, v[82:83]
	v_lshl_add_u64 v[82:83], s[14:15], 0, v[82:83]
	v_lshl_add_u64 v[126:127], v[82:83], 0, v[130:131]
	v_add_co_u32_e32 v144, vcc, s33, v126
	global_load_dwordx4 v[82:85], v[126:127], off
	s_nop 0
	v_addc_co_u32_e32 v145, vcc, 0, v127, vcc
	v_add_co_u32_e32 v166, vcc, s56, v126
	global_load_dwordx4 v[86:89], v[144:145], off
	s_nop 0
	v_addc_co_u32_e32 v167, vcc, 0, v127, vcc
	global_load_dwordx4 v[90:93], v[166:167], off
	global_load_dwordx4 v[94:97], v[48:49], off
	v_add_co_u32_e32 v214, vcc, s57, v126
	v_lshrrev_b32_e32 v123, 4, v122
	s_nop 0
	v_addc_co_u32_e32 v215, vcc, 0, v127, vcc
	global_load_dwordx4 v[98:101], v[214:215], off
	v_xor_b32_e32 v103, v123, v122
	v_lshlrev_b32_e32 v103, 4, v103
	v_and_b32_e32 v103, 0x70, v103
	v_and_or_b32 v130, v102, s22, v103
	global_load_dwordx4 v[102:105], v[48:49], off offset:128
	global_load_dwordx4 v[106:109], v[126:127], off offset:128
	global_load_dwordx4 v[110:113], v[144:145], off offset:128
	global_load_dwordx4 v[114:117], v[166:167], off offset:128
	global_load_dwordx4 v[118:121], v[214:215], off offset:128
	s_barrier
	v_and_b32_e32 v124, 15, v122
	v_bfe_u32 v125, v122, 1, 3
	v_bfe_u32 v136, v122, 4, 2
	v_lshlrev_b32_e32 v137, 5, v122
	v_lshlrev_b32_e32 v124, 7, v124
	v_bitop3_b32 v123, v123, v125, 3 bitop3:0x6c
	v_lshlrev_b32_e32 v122, 6, v122
	v_and_or_b32 v137, v137, s21, v124
	v_lshlrev_b32_e32 v123, 4, v123
	v_and_b32_e32 v122, 0xffffe000, v122
	v_or3_b32 v157, v123, v122, v124
	v_or_b32_e32 v168, v137, v123
	v_bitop3_b32 v123, v136, v125, 4 bitop3:0x36
	v_lshlrev_b32_e32 v123, 4, v123
	v_or3_b32 v197, v123, v122, v124
	v_or_b32_e32 v216, v137, v123
	s_waitcnt vmcnt(6)
	ds_write_b128 v130, v[94:97] offset:16384
	ds_write_b128 v130, v[82:85]
	ds_write_b128 v130, v[86:89] offset:4096
	ds_write_b128 v130, v[90:93] offset:8192
	s_waitcnt vmcnt(5)
	ds_write_b128 v130, v[98:101] offset:12288
	s_waitcnt lgkmcnt(0)
	s_barrier
	global_load_dwordx4 v[82:85], v[144:145], off offset:256
	global_load_dwordx4 v[86:89], v[166:167], off offset:256
	global_load_dwordx4 v[90:93], v[214:215], off offset:256
	global_load_dwordx4 v[94:97], v[126:127], off offset:256
	global_load_dwordx4 v[98:101], v[48:49], off offset:256
	ds_read_b128 v[122:125], v157
	ds_read_b128 v[136:139], v157 offset:2048
	ds_read_b128 v[140:143], v157 offset:4096
	ds_read_b128 v[158:161], v157 offset:6144
	ds_read_b128 v[162:165], v168 offset:16384
	s_setprio 1
	s_waitcnt lgkmcnt(0)
	v_mfma_f32_16x16x32_bf16 v[122:125], v[162:165], v[122:125], 0
	v_mfma_f32_16x16x32_bf16 v[136:139], v[162:165], v[136:139], 0
	v_mfma_f32_16x16x32_bf16 v[140:143], v[162:165], v[140:143], 0
	v_mfma_f32_16x16x32_bf16 v[158:161], v[162:165], v[158:161], 0
	s_setprio 0
	ds_read_b128 v[162:165], v197
	ds_read_b128 v[198:201], v197 offset:2048
	ds_read_b128 v[202:205], v197 offset:4096
	ds_read_b128 v[206:209], v197 offset:6144
	ds_read_b128 v[210:213], v216 offset:16384
	s_setprio 1
	s_waitcnt lgkmcnt(0)
	v_mfma_f32_16x16x32_bf16 v[122:125], v[210:213], v[162:165], v[122:125]
	v_mfma_f32_16x16x32_bf16 v[136:139], v[210:213], v[198:201], v[136:139]
	v_mfma_f32_16x16x32_bf16 v[140:143], v[210:213], v[202:205], v[140:143]
	v_mfma_f32_16x16x32_bf16 v[158:161], v[210:213], v[206:209], v[158:161]
	s_setprio 0
	s_waitcnt vmcnt(8)
	ds_write_b128 v130, v[106:109] offset:32768
	s_waitcnt vmcnt(7)
	ds_write_b128 v130, v[110:113] offset:36864
	s_waitcnt vmcnt(6)
	ds_write_b128 v130, v[114:117] offset:40960
	s_waitcnt vmcnt(5)
	ds_write_b128 v130, v[118:121] offset:45056
	ds_write_b128 v130, v[102:105] offset:49152
	s_waitcnt lgkmcnt(0)
	s_barrier
; #define GLOAD(ra, rb, koff)                                                        \
;   {                                                                                \
;     _Pragma("unroll") for (int j = 0; j < 4; j++) ra[j] = *(const u32x4*)(pa + j * sa32 + (koff));   \
;     _Pragma("unroll") for (int j = 0; j < NB_; j++) rb[j] = *(const u32x4*)(pbv[j] + (koff));         \
;   }
; template <int NT, bool PRE> ...
;     ...
;   if (!PRE) {
;     GLOAD(ra0, rb0, 0);
;     GLOAD(ra1, rb1, 64);
;   }
;   __syncthreads();
;   for (int k0 = 0; k0 < K; k0 += 128) {
;     LSTORE(ra0, rb0, 0);
;     __syncthreads();
;     GLOAD(ra0, rb0, min(k0 + 128, K - 128));
;     __builtin_amdgcn_sched_barrier(0);
;     COMPUTE(0);
;     LSTORE(ra1, rb1, 1);
;     __syncthreads();
;     GLOAD(ra1, rb1, min(k0 + 192, K - 64));
;     __builtin_amdgcn_sched_barrier(0);
;     COMPUTE(1);
; __device__ __forceinline__ void phase_merge(const Params& P, u16* sA, u16* sB) {
;     ...
;     for (int i = 0; i < 4; i++) {
;       f32x4 ap[4][1];
;       zero_acc<1>(ap);
;       gemm_main<1>(Y + i * 256, 1024, (const u16*)(ws + O_WB) + (size_t)i * 1024 * 256, 256, 256, m0, n0, ap, sA, sB);
	global_load_dwordx4 v[102:105], v[144:145], off offset:384
	global_load_dwordx4 v[106:109], v[166:167], off offset:384
	global_load_dwordx4 v[110:113], v[214:215], off offset:384
	global_load_dwordx4 v[114:117], v[126:127], off offset:384
	global_load_dwordx4 v[118:121], v[48:49], off offset:384
	ds_read_b128 v[162:165], v157 offset:32768
	ds_read_b128 v[198:201], v157 offset:34816
	ds_read_b128 v[202:205], v157 offset:36864
	ds_read_b128 v[206:209], v157 offset:38912
	ds_read_b128 v[210:213], v168 offset:49152
	s_setprio 1
	s_waitcnt lgkmcnt(0)
	v_mfma_f32_16x16x32_bf16 v[122:125], v[210:213], v[162:165], v[122:125]
	v_mfma_f32_16x16x32_bf16 v[136:139], v[210:213], v[198:201], v[136:139]
	v_mfma_f32_16x16x32_bf16 v[140:143], v[210:213], v[202:205], v[140:143]
	v_mfma_f32_16x16x32_bf16 v[158:161], v[210:213], v[206:209], v[158:161]
	s_setprio 0
	ds_read_b128 v[162:165], v197 offset:32768
	ds_read_b128 v[198:201], v197 offset:34816
	ds_read_b128 v[202:205], v197 offset:36864
	ds_read_b128 v[206:209], v197 offset:38912
	ds_read_b128 v[210:213], v216 offset:49152
	s_setprio 1
	s_waitcnt lgkmcnt(0)
	v_mfma_f32_16x16x32_bf16 v[122:125], v[210:213], v[162:165], v[122:125]
	v_mfma_f32_16x16x32_bf16 v[136:139], v[210:213], v[198:201], v[136:139]
	v_mfma_f32_16x16x32_bf16 v[140:143], v[210:213], v[202:205], v[140:143]
	v_mfma_f32_16x16x32_bf16 v[158:161], v[210:213], v[206:209], v[158:161]
	s_setprio 0
	s_waitcnt vmcnt(6)
	ds_write_b128 v130, v[94:97]
	ds_write_b128 v130, v[82:85] offset:4096
	ds_write_b128 v130, v[86:89] offset:8192
	ds_write_b128 v130, v[90:93] offset:12288
	s_waitcnt vmcnt(5)
	ds_write_b128 v130, v[98:101] offset:16384
	s_waitcnt lgkmcnt(0)
	s_barrier
	ds_read_b128 v[82:85], v157
	ds_read_b128 v[86:89], v157 offset:2048
	ds_read_b128 v[90:93], v157 offset:4096
	ds_read_b128 v[94:97], v157 offset:6144
	ds_read_b128 v[98:101], v168 offset:16384
	s_setprio 1
	s_waitcnt lgkmcnt(0)
	v_mfma_f32_16x16x32_bf16 v[82:85], v[98:101], v[82:85], v[122:125]
	v_mfma_f32_16x16x32_bf16 v[86:89], v[98:101], v[86:89], v[136:139]
	v_mfma_f32_16x16x32_bf16 v[90:93], v[98:101], v[90:93], v[140:143]
	v_mfma_f32_16x16x32_bf16 v[94:97], v[98:101], v[94:97], v[158:161]
	s_setprio 0
	ds_read_b128 v[98:101], v197
	ds_read_b128 v[122:125], v197 offset:2048
	ds_read_b128 v[136:139], v197 offset:4096
	ds_read_b128 v[140:143], v197 offset:6144
	ds_read_b128 v[158:161], v216 offset:16384
	s_setprio 1
	s_waitcnt lgkmcnt(0)
	v_mfma_f32_16x16x32_bf16 v[82:85], v[158:161], v[98:101], v[82:85]
	v_mfma_f32_16x16x32_bf16 v[86:89], v[158:161], v[122:125], v[86:89]
	v_mfma_f32_16x16x32_bf16 v[90:93], v[158:161], v[136:139], v[90:93]
	v_mfma_f32_16x16x32_bf16 v[94:97], v[158:161], v[140:143], v[94:97]
	s_setprio 0
	s_waitcnt vmcnt(1)
	ds_write_b128 v130, v[114:117] offset:32768
	ds_write_b128 v130, v[102:105] offset:36864
	ds_write_b128 v130, v[106:109] offset:40960
	ds_write_b128 v130, v[110:113] offset:45056
	s_waitcnt vmcnt(0)
	ds_write_b128 v130, v[118:121] offset:49152
	s_waitcnt lgkmcnt(0)
	s_barrier
; __device__ __forceinline__ float bf2f(u16 h) { return __uint_as_float(((unsigned)h) << 16); }
; __device__ __forceinline__ void phase_merge(const Params& P, u16* sA, u16* sB) {
;     ...
; #pragma unroll
;       for (int mi = 0; mi < 4; mi++) {
;         u32x2 q = gp[mi][i];
;         macc[mi][0] += bf2f(q[0] & 0xffff) * ap[mi][0][0];
;         macc[mi][1] += bf2f(q[0] >> 16) * ap[mi][0][1];
;         macc[mi][2] += bf2f(q[1] & 0xffff) * ap[mi][0][2];
;         macc[mi][3] += bf2f(q[1] >> 16) * ap[mi][0][3];
;       }
;     }
;     const int col = n0 + ((tq >> 6) & 1) * 16 + ((tq & 63) >> 4) * 4;
; #pragma unroll
;     for (int mi = 0; mi < 4; mi++) {
;       int row = m0 + ((tq >> 6) >> 1) * 64 + mi * 16 + (tq & 15);
;       *(uint2*)(MM + (size_t)row * 1024 + col) = pack4(macc[mi]);
;     }
	ds_read_b128 v[98:101], v157 offset:32768
	ds_read_b128 v[102:105], v157 offset:34816
	ds_read_b128 v[106:109], v157 offset:36864
	ds_read_b128 v[110:113], v157 offset:38912
	ds_read_b128 v[114:117], v168 offset:49152
	s_setprio 1
	s_waitcnt lgkmcnt(0)
	v_mfma_f32_16x16x32_bf16 v[82:85], v[114:117], v[98:101], v[82:85]
	v_mfma_f32_16x16x32_bf16 v[86:89], v[114:117], v[102:105], v[86:89]
	v_mfma_f32_16x16x32_bf16 v[90:93], v[114:117], v[106:109], v[90:93]
	v_mfma_f32_16x16x32_bf16 v[94:97], v[114:117], v[110:113], v[94:97]
	s_setprio 0
	ds_read_b128 v[98:101], v197 offset:32768
	ds_read_b128 v[102:105], v197 offset:34816
	ds_read_b128 v[106:109], v197 offset:36864
	ds_read_b128 v[110:113], v197 offset:38912
	ds_read_b128 v[114:117], v216 offset:49152
	s_setprio 1
	s_waitcnt lgkmcnt(0)
	v_mfma_f32_16x16x32_bf16 v[82:85], v[114:117], v[98:101], v[82:85]
	v_mfma_f32_16x16x32_bf16 v[86:89], v[114:117], v[102:105], v[86:89]
	v_mfma_f32_16x16x32_bf16 v[90:93], v[114:117], v[106:109], v[90:93]
	v_mfma_f32_16x16x32_bf16 v[94:97], v[114:117], v[110:113], v[94:97]
	s_setprio 0
	v_and_b32_e32 v49, 0xffff0000, v60
	v_lshlrev_b32_e32 v48, 16, v60
	v_pk_fma_f32 v[12:13], v[12:13], v[48:49], 0 op_sel_hi:[1,1,0]
	v_and_b32_e32 v49, 0xffff0000, v56
	v_lshlrev_b32_e32 v48, 16, v56
	v_pk_fma_f32 v[12:13], v[28:29], v[48:49], v[12:13]
	v_and_b32_e32 v29, 0xffff0000, v52
	v_lshlrev_b32_e32 v28, 16, v52
	v_pk_fma_f32 v[12:13], v[44:45], v[28:29], v[12:13]
	v_and_b32_e32 v29, 0xffff0000, v54
	v_lshlrev_b32_e32 v28, 16, v54
	v_pk_fma_f32 v[12:13], v[82:83], v[28:29], v[12:13]
	v_and_b32_e32 v29, 0xffff0000, v61
	v_lshlrev_b32_e32 v28, 16, v61
	v_pk_fma_f32 v[14:15], v[14:15], v[28:29], 0 op_sel_hi:[1,1,0]
	v_and_b32_e32 v29, 0xffff0000, v57
	v_lshlrev_b32_e32 v28, 16, v57
	v_pk_fma_f32 v[14:15], v[30:31], v[28:29], v[14:15]
	v_and_b32_e32 v29, 0xffff0000, v53
	v_lshlrev_b32_e32 v28, 16, v53
	v_pk_fma_f32 v[14:15], v[46:47], v[28:29], v[14:15]
	v_and_b32_e32 v29, 0xffff0000, v50
	v_lshlrev_b32_e32 v28, 16, v50
	v_pk_fma_f32 v[14:15], v[84:85], v[28:29], v[14:15]
	v_and_b32_e32 v29, 0xffff0000, v51
	v_lshlrev_b32_e32 v28, 16, v51
	v_pk_fma_f32 v[8:9], v[8:9], v[28:29], 0 op_sel_hi:[1,1,0]
	v_and_b32_e32 v29, 0xffff0000, v58
	v_lshlrev_b32_e32 v28, 16, v58
	v_pk_fma_f32 v[8:9], v[24:25], v[28:29], v[8:9]
	v_and_b32_e32 v25, 0xffff0000, v62
	v_lshlrev_b32_e32 v24, 16, v62
	v_pk_fma_f32 v[8:9], v[40:41], v[24:25], v[8:9]
	v_and_b32_e32 v25, 0xffff0000, v64
	v_lshlrev_b32_e32 v24, 16, v64
	v_pk_fma_f32 v[8:9], v[86:87], v[24:25], v[8:9]
	v_and_b32_e32 v25, 0xffff0000, v55
	v_lshlrev_b32_e32 v24, 16, v55
	v_pk_fma_f32 v[10:11], v[10:11], v[24:25], 0 op_sel_hi:[1,1,0]
	v_and_b32_e32 v25, 0xffff0000, v59
	v_lshlrev_b32_e32 v24, 16, v59
	v_pk_fma_f32 v[10:11], v[26:27], v[24:25], v[10:11]
	v_and_b32_e32 v25, 0xffff0000, v63
	v_lshlrev_b32_e32 v24, 16, v63
	v_pk_fma_f32 v[10:11], v[42:43], v[24:25], v[10:11]
	v_and_b32_e32 v25, 0xffff0000, v65
	v_lshlrev_b32_e32 v24, 16, v65
	v_pk_fma_f32 v[10:11], v[88:89], v[24:25], v[10:11]
	v_and_b32_e32 v25, 0xffff0000, v66
	v_lshlrev_b32_e32 v24, 16, v66
	v_pk_fma_f32 v[4:5], v[4:5], v[24:25], 0 op_sel_hi:[1,1,0]
	v_and_b32_e32 v25, 0xffff0000, v68
	v_lshlrev_b32_e32 v24, 16, v68
	v_pk_fma_f32 v[4:5], v[20:21], v[24:25], v[4:5]
	v_and_b32_e32 v21, 0xffff0000, v70
	v_lshlrev_b32_e32 v20, 16, v70
	v_pk_fma_f32 v[4:5], v[36:37], v[20:21], v[4:5]
	v_and_b32_e32 v21, 0xffff0000, v72
	v_lshlrev_b32_e32 v20, 16, v72
	v_pk_fma_f32 v[4:5], v[90:91], v[20:21], v[4:5]
	v_and_b32_e32 v21, 0xffff0000, v67
	v_lshlrev_b32_e32 v20, 16, v67
	v_pk_fma_f32 v[6:7], v[6:7], v[20:21], 0 op_sel_hi:[1,1,0]
	v_and_b32_e32 v21, 0xffff0000, v69
	v_lshlrev_b32_e32 v20, 16, v69
	v_pk_fma_f32 v[6:7], v[22:23], v[20:21], v[6:7]
	v_and_b32_e32 v21, 0xffff0000, v71
	v_lshlrev_b32_e32 v20, 16, v71
	v_pk_fma_f32 v[6:7], v[38:39], v[20:21], v[6:7]
	v_and_b32_e32 v21, 0xffff0000, v73
	v_lshlrev_b32_e32 v20, 16, v73
	v_pk_fma_f32 v[6:7], v[92:93], v[20:21], v[6:7]
	v_and_b32_e32 v21, 0xffff0000, v74
	v_lshlrev_b32_e32 v20, 16, v74
	v_pk_fma_f32 v[0:1], v[0:1], v[20:21], 0 op_sel_hi:[1,1,0]
	v_and_b32_e32 v21, 0xffff0000, v76
	v_lshlrev_b32_e32 v20, 16, v76
	v_pk_fma_f32 v[0:1], v[16:17], v[20:21], v[0:1]
	v_and_b32_e32 v17, 0xffff0000, v78
	v_lshlrev_b32_e32 v16, 16, v78
	v_pk_fma_f32 v[0:1], v[32:33], v[16:17], v[0:1]
	v_and_b32_e32 v17, 0xffff0000, v80
	v_lshlrev_b32_e32 v16, 16, v80
	v_pk_fma_f32 v[0:1], v[94:95], v[16:17], v[0:1]
	v_and_b32_e32 v17, 0xffff0000, v75
	v_lshlrev_b32_e32 v16, 16, v75
	v_pk_fma_f32 v[2:3], v[2:3], v[16:17], 0 op_sel_hi:[1,1,0]
	v_and_b32_e32 v17, 0xffff0000, v77
	v_lshlrev_b32_e32 v16, 16, v77
	v_pk_fma_f32 v[2:3], v[18:19], v[16:17], v[2:3]
	v_and_b32_e32 v17, 0xffff0000, v79
	v_lshlrev_b32_e32 v16, 16, v79
	v_pk_fma_f32 v[2:3], v[34:35], v[16:17], v[2:3]
	v_and_b32_e32 v17, 0xffff0000, v81
	v_lshlrev_b32_e32 v16, 16, v81
	v_pk_fma_f32 v[2:3], v[96:97], v[16:17], v[2:3]
	v_or_b32_e32 v16, s20, v149
	v_add_u32_e32 v18, s19, v150
	v_ashrrev_i32_e32 v17, 31, v16
	v_ashrrev_i32_e32 v19, 31, v18
	v_lshl_add_u64 v[16:17], v[16:17], 1, s[2:3]
	v_cvt_pk_bf16_f32 v12, v12, v13
	v_cvt_pk_bf16_f32 v13, v14, v15
	v_lshlrev_b64 v[14:15], 11, v[18:19]
	v_lshl_add_u64 v[14:15], v[16:17], 0, v[14:15]
	global_store_dwordx2 v[14:15], v[12:13], off
	v_or_b32_e32 v12, 16, v18
	v_ashrrev_i32_e32 v13, 31, v12
	v_cvt_pk_bf16_f32 v8, v8, v9
	v_cvt_pk_bf16_f32 v9, v10, v11
	v_lshlrev_b64 v[10:11], 11, v[12:13]
	v_lshl_add_u64 v[10:11], v[16:17], 0, v[10:11]
	global_store_dwordx2 v[10:11], v[8:9], off
	v_or_b32_e32 v8, 32, v18
	v_ashrrev_i32_e32 v9, 31, v8
	v_cvt_pk_bf16_f32 v4, v4, v5
	v_cvt_pk_bf16_f32 v5, v6, v7
	v_lshlrev_b64 v[6:7], 11, v[8:9]
	v_lshl_add_u64 v[6:7], v[16:17], 0, v[6:7]
	global_store_dwordx2 v[6:7], v[4:5], off
	v_or_b32_e32 v4, 48, v18
	v_ashrrev_i32_e32 v5, 31, v4
	v_cvt_pk_bf16_f32 v0, v0, v1
	v_cvt_pk_bf16_f32 v1, v2, v3
	v_lshlrev_b64 v[2:3], 11, v[4:5]
	s_add_i32 s18, s18, s90
	v_lshl_add_u64 v[2:3], v[16:17], 0, v[2:3]
	s_cmpk_lt_i32 s18, 0x1080
	global_store_dwordx2 v[2:3], v[0:1], off
	s_cbranch_scc1 .LBB0_1988
